# de-serialised loads: ctx-row loops of R3/R4 (27-28 loads issued together instead of 24 load+wait steps) and Fourier stage-2 gain gathers (64 loads hoisted to item top)
# speedup vs baseline: 1.0078x; 1.0028x over previous
; __device__ __forceinline__ unsigned cvt_pk_bf16(float lo, float hi) { unsigned r; asm volatile("v_cvt_pk_bf16_f32 %0, %1, %2" : "=v"(r) : "v"(lo), "v"(hi)); return r; }
; __host__ __device__ __forceinline__ int fsig(int p) { return (p & 1) ? ((p == 1) ? 32 : 64 - (p >> 1)) : (p >> 1); }
; __device__ __forceinline__ void fourier_stage2(LAS unsigned char* lds, int wave, const bf16* Tp, bf16* MIX, const float* gmix, int gw, int NGW, int lane) {
;     ...
;         const bf16* ap = Tp + (size_t)trow * 32768 + ((size_t)(b * 256 + k2) * 16 + s2b);
;         bf16x8 af[16];
; #pragma unroll
;         for (int t = 0; t < 16; ++t) af[t] = *(const bf16x8*)(ap + t * 256);
;         f32x4 y[16]; float ss = 0.f;
; #pragma unroll
;         for (int t = 0; t < 16; ++t) {
;             const f32x4 z4 = {0.f, 0.f, 0.f, 0.f};
;             const f32x4 aR = __builtin_amdgcn_mfma_f32_16x16x32_bf16(af[t], bR, z4, 0, 0, 0), aI = __builtin_amdgcn_mfma_f32_16x16x32_bf16(af[t], bI, z4, 0, 0, 0);
;             const bool special = ((t & 3) == 0) && kq == 0;
;             const float p0 = aR[0] * NRM, p1 = (special ? aR[1] : aI[1]) * NRM, p2 = aR[2] * NRM, p3 = aI[3] * NRM;
;             f32x4 o; o[0] = special ? p0 : p0 + p1; o[1] = special ? p1 : p0 - p1; o[2] = p2 + p3; o[3] = p2 - p3;
;             y[t] = o; ss += (o[0] * o[0] + o[1] * o[1]) + (o[2] * o[2] + o[3] * o[3]); }
;     ...
;         for (int t = 0; t < 16; ++t) { const float* gb = gmix + 768 + (t >> 2) * 64; const int p = 16 * (t & 3) + 4 * kq;
;             v2u w; w.x = cvt_pk_bf16(y[t][0] * rn * gb[fsig(p)], y[t][1] * rn * gb[fsig(p + 1)]); w.y = cvt_pk_bf16(y[t][2] * rn * gb[fsig(p + 2)], y[t][3] * rn * gb[fsig(p + 3)]);
.LBB0_468:
	s_or_b64 exec, exec, s[0:1]
	global_load_dword v182, v[32:33], off offset:3072
	global_load_dword v183, v[34:35], off offset:3072
	global_load_dword v184, v[32:33], off offset:3076
	global_load_dword v185, v[36:37], off offset:3324
	global_load_dword v186, v[38:39], off offset:3072
	global_load_dword v187, v[40:41], off offset:3072
	global_load_dword v188, v[38:39], off offset:3076
	global_load_dword v189, v[42:43], off offset:3324
	global_load_dword v190, v[44:45], off offset:3072
	global_load_dword v191, v[46:47], off offset:3072
	global_load_dword v192, v[44:45], off offset:3076
	global_load_dword v193, v[48:49], off offset:3324
	global_load_dword v194, v[50:51], off offset:3072
	global_load_dword v195, v[52:53], off offset:3072
	global_load_dword v196, v[50:51], off offset:3076
	global_load_dword v197, v[54:55], off offset:3324
	global_load_dword v198, v[32:33], off offset:3328
	global_load_dword v199, v[34:35], off offset:3328
	global_load_dword v200, v[32:33], off offset:3332
	global_load_dword v201, v[36:37], off offset:3580
	global_load_dword v202, v[38:39], off offset:3328
	global_load_dword v203, v[40:41], off offset:3328
	global_load_dword v204, v[38:39], off offset:3332
	global_load_dword v205, v[42:43], off offset:3580
	global_load_dword v206, v[44:45], off offset:3328
	global_load_dword v207, v[46:47], off offset:3328
	global_load_dword v208, v[44:45], off offset:3332
	global_load_dword v209, v[48:49], off offset:3580
	global_load_dword v210, v[50:51], off offset:3328
	global_load_dword v211, v[52:53], off offset:3328
	global_load_dword v212, v[50:51], off offset:3332
	global_load_dword v213, v[54:55], off offset:3580
	global_load_dword v214, v[32:33], off offset:3584
	global_load_dword v215, v[34:35], off offset:3584
	global_load_dword v216, v[32:33], off offset:3588
	global_load_dword v217, v[36:37], off offset:3836
	global_load_dword v218, v[38:39], off offset:3584
	global_load_dword v219, v[40:41], off offset:3584
	global_load_dword v220, v[38:39], off offset:3588
	global_load_dword v221, v[42:43], off offset:3836
	global_load_dword v164, v[44:45], off offset:3584
	global_load_dword v165, v[46:47], off offset:3584
	global_load_dword v166, v[44:45], off offset:3588
	global_load_dword v167, v[48:49], off offset:3836
	global_load_dword v168, v[50:51], off offset:3584
	global_load_dword v169, v[52:53], off offset:3584
	global_load_dword v170, v[50:51], off offset:3588
	global_load_dword v171, v[54:55], off offset:3836
	global_load_dword v172, v[32:33], off offset:3840
	global_load_dword v173, v[34:35], off offset:3840
	global_load_dword v174, v[32:33], off offset:3844
	global_load_dword v175, v[36:37], off offset:4092
	global_load_dword v222, v[38:39], off offset:3840
	global_load_dword v223, v[40:41], off offset:3840
	global_load_dword v224, v[38:39], off offset:3844
	global_load_dword v225, v[42:43], off offset:4092
	global_load_dword v226, v[44:45], off offset:3840
	global_load_dword v227, v[46:47], off offset:3840
	global_load_dword v242, v[44:45], off offset:3844
	global_load_dword v243, v[48:49], off offset:4092
	global_load_dword v244, v[50:51], off offset:3840
	global_load_dword v245, v[52:53], off offset:3840
	global_load_dword v246, v[50:51], off offset:3844
	global_load_dword v247, v[54:55], off offset:4092
	v_ashrrev_i32_e32 v9, 31, v8
	v_lshlrev_b64 v[8:9], 16, v[8:9]
	v_lshl_add_u64 v[20:21], v[72:73], 0, v[8:9]
	global_load_dwordx4 v[8:11], v[20:21], off
	global_load_dwordx4 v[12:15], v[20:21], off offset:512
	global_load_dwordx4 v[16:19], v[20:21], off offset:1024
	global_load_dwordx4 v[80:83], v[20:21], off offset:1536
	global_load_dwordx4 v[96:99], v[20:21], off offset:2048
	global_load_dwordx4 v[106:109], v[20:21], off offset:2560
	global_load_dwordx4 v[122:125], v[20:21], off offset:3072
	global_load_dwordx4 v[126:129], v[20:21], off offset:3584
	v_mov_b32_e32 v149, v181
	v_mov_b32_e32 v157, v181
	v_mov_b32_e32 v159, v181
	v_mov_b32_e32 v147, v181
	s_ashr_i32 s1, s11, 31
	s_add_u32 s0, s22, s11
	s_addc_u32 s1, 0, s1
	s_add_i32 s10, s10, s96
	s_cmpk_lt_i32 s10, 0x1000
	s_waitcnt vmcnt(7)
	v_mfma_f32_16x16x32_bf16 v[76:79], v[8:11], v[0:3], 0
	v_mfma_f32_16x16x32_bf16 v[84:87], v[8:11], v[4:7], 0
	v_add_co_u32_e32 v8, vcc, 0x1000, v20
	s_nop 1
	v_addc_co_u32_e32 v9, vcc, 0, v21, vcc
	global_load_dwordx4 v[134:137], v[8:9], off
	global_load_dwordx4 v[138:141], v[8:9], off offset:512
	global_load_dwordx4 v[28:31], v[8:9], off offset:1024
	global_load_dwordx4 v[24:27], v[8:9], off offset:1536
	s_waitcnt vmcnt(10)
	v_mfma_f32_16x16x32_bf16 v[92:95], v[12:15], v[0:3], 0
	v_cndmask_b32_e64 v77, v85, v77, s[6:7]
	v_mov_b32_e32 v79, v87
	v_mfma_f32_16x16x32_bf16 v[88:91], v[12:15], v[4:7], 0
	s_waitcnt vmcnt(9)
	v_mfma_f32_16x16x32_bf16 v[100:103], v[16:19], v[0:3], 0
	s_nop 2
	v_mov_b32_e32 v93, v181
	s_nop 1
	v_mov_b32_e32 v95, v91
	v_mfma_f32_16x16x32_bf16 v[110:113], v[16:19], v[4:7], 0
	global_load_dwordx4 v[20:23], v[8:9], off offset:2048
	global_load_dwordx4 v[16:19], v[8:9], off offset:2560
	global_load_dwordx4 v[12:15], v[8:9], off offset:3072
	s_nop 0
	global_load_dwordx4 v[8:11], v[8:9], off offset:3584
	s_nop 2
	v_mov_b32_e32 v101, v111
	s_waitcnt vmcnt(12)
; __device__ __forceinline__ void fourier_stage2(LAS unsigned char* lds, int wave, const bf16* Tp, bf16* MIX, const float* gmix, int gw, int NGW, int lane) {
;     ...
;         for (int t = 0; t < 16; ++t) {
;             const f32x4 z4 = {0.f, 0.f, 0.f, 0.f};
;             const f32x4 aR = __builtin_amdgcn_mfma_f32_16x16x32_bf16(af[t], bR, z4, 0, 0, 0), aI = __builtin_amdgcn_mfma_f32_16x16x32_bf16(af[t], bI, z4, 0, 0, 0);
;             const bool special = ((t & 3) == 0) && kq == 0;
;             const float p0 = aR[0] * NRM, p1 = (special ? aR[1] : aI[1]) * NRM, p2 = aR[2] * NRM, p3 = aI[3] * NRM;
;             f32x4 o; o[0] = special ? p0 : p0 + p1; o[1] = special ? p1 : p0 - p1; o[2] = p2 + p3; o[3] = p2 - p3;
;             y[t] = o; ss += (o[0] * o[0] + o[1] * o[1]) + (o[2] * o[2] + o[3] * o[3]); }
	v_mfma_f32_16x16x32_bf16 v[142:145], v[80:83], v[4:7], 0
	v_mov_b32_e32 v103, v113
	v_mul_f32_e32 v84, 0x3ab504f3, v111
	v_mul_f32_e32 v86, 0x3ab504f3, v113
	v_mfma_f32_16x16x32_bf16 v[114:117], v[80:83], v[0:3], 0
	v_mul_f32_e32 v80, 0x3ab504f3, v87
	v_mul_f32_e32 v81, 0x3ab504f3, v89
	v_mul_f32_e32 v82, 0x3ab504f3, v91
	v_pk_mul_f32 v[110:111], v[76:77], s[54:55] op_sel_hi:[1, 0]
	v_pk_fma_f32 v[120:121], v[78:79], s[54:55], v[80:81] op_sel_hi:[1, 0, 0]
	s_nop 2
	v_mov_b32_e32 v115, v143
	v_pk_fma_f32 v[118:119], v[78:79], s[54:55], v[80:81] op_sel_hi:[1, 0, 0] neg_lo:[0, 0, 1] neg_hi:[0, 0, 1]
	v_pk_fma_f32 v[90:91], v[94:95], s[54:55], v[82:83] op_sel_hi:[1, 0, 0]
	v_pk_fma_f32 v[88:89], v[94:95], s[54:55], v[82:83] op_sel_hi:[1, 0, 0] neg_lo:[0, 0, 1] neg_hi:[0, 0, 1]
	v_fma_f32 v105, v92, s54, -v81
	v_pk_fma_f32 v[82:83], v[100:101], s[54:55], v[84:85] op_sel_hi:[1, 0, 0] neg_lo:[0, 0, 1] neg_hi:[0, 0, 1]
	v_pk_fma_f32 v[76:77], v[102:103], s[54:55], v[86:87] op_sel_hi:[1, 0, 0]
	v_pk_fma_f32 v[78:79], v[102:103], s[54:55], v[86:87] op_sel_hi:[1, 0, 0] neg_lo:[0, 0, 1] neg_hi:[0, 0, 1]
	v_sub_f32_e32 v102, v110, v111
	v_fmamk_f32 v104, v92, 0x3ab504f3, v81
	v_pk_fma_f32 v[80:81], v[100:101], s[54:55], v[84:85] op_sel_hi:[1, 0, 0]
	v_pk_mul_f32 v[84:85], v[114:115], s[54:55] op_sel_hi:[1, 0]
	v_add_f32_e32 v87, v110, v111
	v_mul_f32_e32 v86, v105, v105
	v_pk_mul_f32 v[94:95], v[82:83], v[82:83]
	v_pk_mul_f32 v[100:101], v[78:79], v[78:79]
	v_mov_b32_e32 v89, v145
	v_mov_b32_e32 v92, v88
	v_cndmask_b32_e64 v130, v102, v111, s[6:7]
	v_mov_b32_e32 v131, v145
	v_add_f32_e32 v79, v84, v85
	v_sub_f32_e32 v83, v84, v85
	v_mov_b32_e32 v91, v116
	v_mov_b32_e32 v148, v90
	v_mov_b32_e32 v119, v145
	v_mov_b32_e32 v156, v118
	v_cndmask_b32_e64 v132, v87, v110, s[6:7]
	v_pk_fma_f32 v[102:103], v[104:105], v[104:105], v[86:87] op_sel_hi:[1, 1, 0]
	v_pk_mul_f32 v[86:87], v[88:89], v[92:93]
	v_pk_fma_f32 v[92:93], v[76:77], v[76:77], v[100:101]
	v_pk_fma_f32 v[94:95], v[80:81], v[80:81], v[94:95]
	v_mov_b32_e32 v158, v130
	v_mov_b32_e32 v133, v116
	v_mov_b32_e32 v121, v116
	v_mov_b32_e32 v180, v120
	v_pk_mul_f32 v[84:85], v[118:119], v[156:157]
	v_mov_b32_e32 v146, v132
	v_pk_fma_f32 v[100:101], v[90:91], v[148:149], v[86:87]
	v_pk_fma_f32 v[86:87], v[90:91], v[148:149], v[86:87] neg_lo:[0, 0, 1] neg_hi:[0, 0, 1]
	v_mul_f32_e32 v93, v79, v79
	v_mul_f32_e32 v95, v83, v83
	v_pk_mul_f32 v[110:111], v[130:131], v[158:159]
	v_pk_fma_f32 v[84:85], v[120:121], v[180:181], v[84:85]
	v_pk_add_f32 v[112:113], v[92:93], v[94:95]
	v_pk_add_f32 v[100:101], v[100:101], v[102:103]
	v_pk_mul_f32 v[92:93], v[86:87], v[86:87]
	v_pk_fma_f32 v[94:95], v[132:133], v[146:147], v[110:111]
	v_mov_b32_e32 v101, v93
	v_pk_add_f32 v[102:103], v[84:85], v[94:95]
	v_pk_mul_f32 v[92:93], v[84:85], v[94:95]
	s_nop 0
	v_mov_b32_e32 v103, v93
	s_waitcnt vmcnt(11)
	v_mfma_f32_16x16x32_bf16 v[92:95], v[96:99], v[0:3], 0
	v_add_f32_e64 v100, v102, v100
	v_add_f32_e64 v101, v103, v101
	v_pk_add_f32 v[100:101], v[100:101], v[112:113]
	v_mfma_f32_16x16x32_bf16 v[96:99], v[96:99], v[4:7], 0
	v_add_f32_e64 v142, v100, v101
	v_add_f32_e64 v143, v101, v100
	s_nop 5
	v_cndmask_b32_e64 v93, v97, v93, s[6:7]
	v_pk_mul_f32 v[92:93], v[92:93], s[54:55] op_sel_hi:[1, 0]
	v_mov_b32_e32 v95, v99
	v_add_f32_e32 v77, v92, v93
	v_cndmask_b32_e64 v84, v77, v92, s[6:7]
	v_sub_f32_e32 v77, v92, v93
	v_mul_f32_e32 v92, 0x3ab504f3, v99
	v_cndmask_b32_e64 v86, v77, v93, s[6:7]
	v_pk_fma_f32 v[100:101], v[94:95], s[54:55], v[92:93] op_sel_hi:[1, 0, 0] neg_lo:[0, 0, 1] neg_hi:[0, 0, 1]
	v_pk_fma_f32 v[102:103], v[94:95], s[54:55], v[92:93] op_sel_hi:[1, 0, 0]
	v_mov_b32_e32 v101, v86
	v_mov_b32_e32 v103, v84
	v_pk_mul_f32 v[96:97], v[100:101], v[100:101]
	s_waitcnt vmcnt(10)
	v_mfma_f32_16x16x32_bf16 v[92:95], v[106:109], v[0:3], 0
	v_fma_f32 v96, v102, v102, v96
	v_fma_f32 v97, v103, v103, v97
	v_pk_add_f32 v[144:145], v[96:97], v[96:97] op_sel:[0, 1] op_sel_hi:[1, 0]
	v_mfma_f32_16x16x32_bf16 v[96:99], v[106:109], v[4:7], 0
	v_add_f32_e64 v142, v142, v144
	v_add_f32_e64 v143, v143, v145
	s_waitcnt vmcnt(9)
	v_mfma_f32_16x16x32_bf16 v[106:109], v[122:125], v[0:3], 0
	s_nop 3
	v_mov_b32_e32 v93, v97
	v_mul_f32_e32 v96, 0x3ab504f3, v97
	v_mov_b32_e32 v95, v99
	v_pk_fma_f32 v[116:117], v[92:93], s[54:55], v[96:97] op_sel_hi:[1, 0, 0]
	v_pk_fma_f32 v[114:115], v[92:93], s[54:55], v[96:97] op_sel_hi:[1, 0, 0] neg_lo:[0, 0, 1] neg_hi:[0, 0, 1]
	v_mul_f32_e32 v92, 0x3ab504f3, v99
	v_pk_fma_f32 v[112:113], v[94:95], s[54:55], v[92:93] op_sel_hi:[1, 0, 0]
	v_pk_fma_f32 v[110:111], v[94:95], s[54:55], v[92:93] op_sel_hi:[1, 0, 0] neg_lo:[0, 0, 1] neg_hi:[0, 0, 1]
	v_mfma_f32_16x16x32_bf16 v[92:95], v[122:125], v[4:7], 0
	v_mov_b32_e32 v180, v112
	s_waitcnt vmcnt(8)
; __device__ __forceinline__ void fourier_stage2(LAS unsigned char* lds, int wave, const bf16* Tp, bf16* MIX, const float* gmix, int gw, int NGW, int lane) {
;     ...
;         for (int t = 0; t < 16; ++t) {
;             const f32x4 z4 = {0.f, 0.f, 0.f, 0.f};
;             const f32x4 aR = __builtin_amdgcn_mfma_f32_16x16x32_bf16(af[t], bR, z4, 0, 0, 0), aI = __builtin_amdgcn_mfma_f32_16x16x32_bf16(af[t], bI, z4, 0, 0, 0);
;             const bool special = ((t & 3) == 0) && kq == 0;
;             const float p0 = aR[0] * NRM, p1 = (special ? aR[1] : aI[1]) * NRM, p2 = aR[2] * NRM, p3 = aI[3] * NRM;
;             f32x4 o; o[0] = special ? p0 : p0 + p1; o[1] = special ? p1 : p0 - p1; o[2] = p2 + p3; o[3] = p2 - p3;
;             y[t] = o; ss += (o[0] * o[0] + o[1] * o[1]) + (o[2] * o[2] + o[3] * o[3]); }
	v_mfma_f32_16x16x32_bf16 v[122:125], v[126:129], v[0:3], 0
	s_nop 4
	v_mov_b32_e32 v107, v93
	v_mov_b32_e32 v109, v95
	v_mul_f32_e32 v92, 0x3ab504f3, v93
	v_mul_f32_e32 v94, 0x3ab504f3, v95
	v_pk_fma_f32 v[96:97], v[106:107], s[54:55], v[92:93] op_sel_hi:[1, 0, 0]
	v_pk_fma_f32 v[98:99], v[106:107], s[54:55], v[92:93] op_sel_hi:[1, 0, 0] neg_lo:[0, 0, 1] neg_hi:[0, 0, 1]
	v_pk_fma_f32 v[92:93], v[108:109], s[54:55], v[94:95] op_sel_hi:[1, 0, 0]
	v_pk_fma_f32 v[94:95], v[108:109], s[54:55], v[94:95] op_sel_hi:[1, 0, 0] neg_lo:[0, 0, 1] neg_hi:[0, 0, 1]
	v_mfma_f32_16x16x32_bf16 v[106:109], v[126:129], v[4:7], 0
	v_mov_b32_e32 v113, v124
	v_mov_b32_e32 v117, v124
	v_pk_mul_f32 v[146:147], v[98:99], v[98:99]
	v_pk_mul_f32 v[148:149], v[94:95], v[94:95]
	v_pk_fma_f32 v[126:127], v[96:97], v[96:97], v[146:147]
	s_nop 2
	v_mov_b32_e32 v123, v107
	v_pk_mul_f32 v[106:107], v[122:123], s[54:55] op_sel_hi:[1, 0]
	v_mov_b32_e32 v111, v109
	v_add_f32_e32 v77, v106, v107
	v_sub_f32_e32 v81, v106, v107
	v_mov_b32_e32 v106, v110
	v_mov_b32_e32 v107, v181
	v_pk_mul_f32 v[124:125], v[110:111], v[106:107]
	v_mov_b32_e32 v115, v109
	v_mov_b32_e32 v106, v114
	v_mov_b32_e32 v122, v116
	v_mov_b32_e32 v123, v181
	v_pk_mul_f32 v[108:109], v[114:115], v[106:107]
	v_pk_fma_f32 v[106:107], v[112:113], v[180:181], v[124:125]
	v_pk_fma_f32 v[122:123], v[116:117], v[122:123], v[108:109]
	v_pk_fma_f32 v[108:109], v[112:113], v[180:181], v[124:125] neg_lo:[0, 0, 1] neg_hi:[0, 0, 1]
	v_pk_add_f32 v[128:129], v[106:107], v[122:123]
	v_pk_mul_f32 v[122:123], v[106:107], v[122:123]
	v_pk_fma_f32 v[124:125], v[92:93], v[92:93], v[148:149]
	v_mov_b32_e32 v129, v123
	v_pk_mul_f32 v[122:123], v[108:109], v[108:109]
	v_mul_f32_e32 v125, v77, v77
	v_mul_f32_e32 v127, v81, v81
	v_mov_b32_e32 v143, v123
	v_pk_add_f32 v[126:127], v[124:125], v[126:127]
	v_pk_add_f32 v[128:129], v[128:129], v[142:143]
	s_waitcnt vmcnt(7)
	v_mfma_f32_16x16x32_bf16 v[122:125], v[134:137], v[0:3], 0
	v_add_f32_e64 v126, v128, v126
	v_add_f32_e64 v127, v129, v127
	v_pk_add_f32 v[156:157], v[126:127], v[126:127] op_sel:[0, 1] op_sel_hi:[1, 0]
	v_mfma_f32_16x16x32_bf16 v[126:129], v[134:137], v[4:7], 0
	s_waitcnt vmcnt(5)
	v_mfma_f32_16x16x32_bf16 v[142:145], v[28:31], v[0:3], 0
	v_mfma_f32_16x16x32_bf16 v[28:31], v[28:31], v[4:7], 0
	s_nop 4
	v_cndmask_b32_e64 v123, v127, v123, s[6:7]
	v_pk_mul_f32 v[122:123], v[122:123], s[54:55] op_sel_hi:[1, 0]
	v_mov_b32_e32 v125, v129
	v_add_f32_e32 v89, v122, v123
	v_cndmask_b32_e64 v91, v89, v122, s[6:7]
	v_sub_f32_e32 v89, v122, v123
	v_mul_f32_e32 v106, 0x3ab504f3, v129
	v_cndmask_b32_e64 v93, v89, v123, s[6:7]
	v_pk_fma_f32 v[126:127], v[124:125], s[54:55], v[106:107] op_sel_hi:[1, 0, 0] neg_lo:[0, 0, 1] neg_hi:[0, 0, 1]
	v_pk_fma_f32 v[128:129], v[124:125], s[54:55], v[106:107] op_sel_hi:[1, 0, 0]
	v_mov_b32_e32 v127, v93
	v_mov_b32_e32 v129, v91
	v_pk_mul_f32 v[134:135], v[126:127], v[126:127]
	v_mfma_f32_16x16x32_bf16 v[122:125], v[138:141], v[0:3], 0
	v_fma_f32 v134, v128, v128, v134
	v_fma_f32 v135, v129, v129, v135
	v_mov_b32_e32 v143, v29
	v_pk_add_f32 v[158:159], v[134:135], v[134:135] op_sel:[0, 1] op_sel_hi:[1, 0]
	v_mfma_f32_16x16x32_bf16 v[134:137], v[138:141], v[4:7], 0
	v_mov_b32_e32 v145, v31
	v_mul_f32_e32 v28, 0x3ab504f3, v29
	v_mul_f32_e32 v30, 0x3ab504f3, v31
	s_waitcnt vmcnt(4)
	v_mfma_f32_16x16x32_bf16 v[146:149], v[24:27], v[0:3], 0
	v_mfma_f32_16x16x32_bf16 v[24:27], v[24:27], v[4:7], 0
	s_nop 1
	v_mov_b32_e32 v123, v135
	v_mul_f32_e32 v106, 0x3ab504f3, v135
	v_mov_b32_e32 v125, v137
	v_pk_fma_f32 v[140:141], v[122:123], s[54:55], v[106:107] op_sel_hi:[1, 0, 0]
	v_pk_fma_f32 v[138:139], v[122:123], s[54:55], v[106:107] op_sel_hi:[1, 0, 0] neg_lo:[0, 0, 1] neg_hi:[0, 0, 1]
	v_mul_f32_e32 v106, 0x3ab504f3, v137
	v_mov_b32_e32 v147, v25
	v_pk_fma_f32 v[136:137], v[124:125], s[54:55], v[106:107] op_sel_hi:[1, 0, 0]
	v_pk_fma_f32 v[134:135], v[124:125], s[54:55], v[106:107] op_sel_hi:[1, 0, 0] neg_lo:[0, 0, 1] neg_hi:[0, 0, 1]
	v_pk_fma_f32 v[122:123], v[142:143], s[54:55], v[28:29] op_sel_hi:[1, 0, 0]
	v_pk_fma_f32 v[124:125], v[142:143], s[54:55], v[28:29] op_sel_hi:[1, 0, 0] neg_lo:[0, 0, 1] neg_hi:[0, 0, 1]
	v_pk_fma_f32 v[28:29], v[144:145], s[54:55], v[30:31] op_sel_hi:[1, 0, 0]
	v_pk_fma_f32 v[30:31], v[144:145], s[54:55], v[30:31] op_sel_hi:[1, 0, 0] neg_lo:[0, 0, 1] neg_hi:[0, 0, 1]
	v_pk_mul_f32 v[24:25], v[146:147], s[54:55] op_sel_hi:[1, 0]
	v_pk_mul_f32 v[144:145], v[30:31], v[30:31]
	v_add_f32_e32 v31, v24, v25
	v_sub_f32_e32 v89, v24, v25
	v_mov_b32_e32 v135, v27
	v_mov_b32_e32 v24, v134
	v_mov_b32_e32 v25, v181
	v_pk_mul_f32 v[142:143], v[124:125], v[124:125]
	v_mov_b32_e32 v137, v148
	v_mov_b32_e32 v141, v148
	v_pk_mul_f32 v[148:149], v[134:135], v[24:25]
	v_mov_b32_e32 v139, v27
	v_mov_b32_e32 v24, v138
	v_mov_b32_e32 v180, v136
	v_mov_b32_e32 v146, v140
	v_mov_b32_e32 v147, v181
	v_pk_mul_f32 v[26:27], v[138:139], v[24:25]
	v_pk_fma_f32 v[144:145], v[28:29], v[28:29], v[144:145]
	v_pk_fma_f32 v[142:143], v[122:123], v[122:123], v[142:143]
	v_pk_fma_f32 v[24:25], v[136:137], v[180:181], v[148:149]
	v_pk_fma_f32 v[146:147], v[140:141], v[146:147], v[26:27]
	v_mul_f32_e32 v145, v31, v31
	v_mul_f32_e32 v143, v89, v89
	v_pk_fma_f32 v[26:27], v[136:137], v[180:181], v[148:149] neg_lo:[0, 0, 1] neg_hi:[0, 0, 1]
	v_pk_add_f32 v[148:149], v[144:145], v[142:143]
	v_pk_add_f32 v[160:161], v[24:25], v[146:147]
	v_pk_mul_f32 v[142:143], v[24:25], v[146:147]
	v_pk_add_f32 v[146:147], v[156:157], v[158:159]
	v_mov_b32_e32 v161, v143
	v_pk_mul_f32 v[142:143], v[26:27], v[26:27]
	s_waitcnt vmcnt(1)
; __device__ __forceinline__ unsigned cvt_pk_bf16(float lo, float hi) { unsigned r; asm volatile("v_cvt_pk_bf16_f32 %0, %1, %2" : "=v"(r) : "v"(lo), "v"(hi)); return r; }
; #define LAS __attribute__((address_space(3)))
; __host__ __device__ __forceinline__ int fsig(int p) { return (p & 1) ? ((p == 1) ? 32 : 64 - (p >> 1)) : (p >> 1); }
; __device__ __forceinline__ void fourier_stage2(LAS unsigned char* lds, int wave, const bf16* Tp, bf16* MIX, const float* gmix, int gw, int NGW, int lane) {
;     ...
;             y[t] = o; ss += (o[0] * o[0] + o[1] * o[1]) + (o[2] * o[2] + o[3] * o[3]); }
;         ss += __shfl_xor(ss, 16); ss += __shfl_xor(ss, 32);
;         const float rn = rsqrtf(ss * (1.f / 256.f) + EPSN);
; #pragma unroll
;         for (int t = 0; t < 16; ++t) { const float* gb = gmix + 768 + (t >> 2) * 64; const int p = 16 * (t & 3) + 4 * kq;
;             v2u w; w.x = cvt_pk_bf16(y[t][0] * rn * gb[fsig(p)], y[t][1] * rn * gb[fsig(p + 1)]); w.y = cvt_pk_bf16(y[t][2] * rn * gb[fsig(p + 2)], y[t][3] * rn * gb[fsig(p + 3)]);
;             *(LAS v2u*)(slab + k2 * 264 + 16 * t + 4 * kq) = w; }
	v_mfma_f32_16x16x32_bf16 v[156:159], v[12:15], v[0:3], 0
	v_mov_b32_e32 v147, v143
	v_pk_add_f32 v[146:147], v[160:161], v[146:147]
	v_mfma_f32_16x16x32_bf16 v[142:145], v[20:23], v[0:3], 0
	v_add_f32_e64 v146, v146, v148
	v_add_f32_e64 v147, v147, v149
	v_pk_add_f32 v[160:161], v[146:147], v[146:147] op_sel:[0, 1] op_sel_hi:[1, 0]
	v_mfma_f32_16x16x32_bf16 v[20:23], v[20:23], v[4:7], 0
	v_mfma_f32_16x16x32_bf16 v[146:149], v[16:19], v[0:3], 0
	v_mfma_f32_16x16x32_bf16 v[16:19], v[16:19], v[4:7], 0
	s_nop 5
	v_cndmask_b32_e64 v143, v21, v143, s[6:7]
	v_pk_mul_f32 v[20:21], v[142:143], s[54:55] op_sel_hi:[1, 0]
	v_mov_b32_e32 v145, v23
	v_add_f32_e32 v22, v20, v21
	v_cndmask_b32_e64 v26, v22, v20, s[6:7]
	v_sub_f32_e32 v20, v20, v21
	v_cndmask_b32_e64 v29, v20, v21, s[6:7]
	v_mul_f32_e32 v20, 0x3ab504f3, v23
	v_pk_fma_f32 v[22:23], v[144:145], s[54:55], v[20:21] op_sel_hi:[1, 0, 0]
	v_pk_fma_f32 v[20:21], v[144:145], s[54:55], v[20:21] op_sel_hi:[1, 0, 0] neg_lo:[0, 0, 1] neg_hi:[0, 0, 1]
	v_mov_b32_e32 v23, v26
	v_mov_b32_e32 v21, v29
	v_pk_mul_f32 v[142:143], v[20:21], v[20:21]
	v_pk_fma_f32 v[142:143], v[22:23], v[22:23], v[142:143]
	v_mfma_f32_16x16x32_bf16 v[12:15], v[12:15], v[4:7], 0
	v_mov_b32_e32 v147, v17
	v_mul_f32_e32 v16, 0x3ab504f3, v17
	v_pk_add_f32 v[162:163], v[142:143], v[142:143] op_sel:[0, 1] op_sel_hi:[1, 0]
	s_waitcnt vmcnt(0)
	v_mfma_f32_16x16x32_bf16 v[4:7], v[8:11], v[4:7], 0
	v_mov_b32_e32 v149, v19
	v_pk_fma_f32 v[144:145], v[146:147], s[54:55], v[16:17] op_sel_hi:[1, 0, 0]
	v_pk_fma_f32 v[142:143], v[146:147], s[54:55], v[16:17] op_sel_hi:[1, 0, 0] neg_lo:[0, 0, 1] neg_hi:[0, 0, 1]
	v_mfma_f32_16x16x32_bf16 v[0:3], v[8:11], v[0:3], 0
	v_mul_f32_e32 v16, 0x3ab504f3, v19
	v_pk_fma_f32 v[18:19], v[148:149], s[54:55], v[16:17] op_sel_hi:[1, 0, 0]
	v_pk_fma_f32 v[16:17], v[148:149], s[54:55], v[16:17] op_sel_hi:[1, 0, 0] neg_lo:[0, 0, 1] neg_hi:[0, 0, 1]
	v_mov_b32_e32 v157, v13
	v_mov_b32_e32 v159, v15
	s_nop 2
	v_mov_b32_e32 v1, v5
	v_mul_f32_e32 v14, 0x3ab504f3, v13
	v_mul_f32_e32 v24, 0x3ab504f3, v15
	v_pk_mul_f32 v[0:1], v[0:1], s[54:55] op_sel_hi:[1, 0]
	v_pk_fma_f32 v[12:13], v[156:157], s[54:55], v[14:15] op_sel_hi:[1, 0, 0]
	v_pk_fma_f32 v[148:149], v[156:157], s[54:55], v[14:15] op_sel_hi:[1, 0, 0] neg_lo:[0, 0, 1] neg_hi:[0, 0, 1]
	v_pk_fma_f32 v[14:15], v[158:159], s[54:55], v[24:25] op_sel_hi:[1, 0, 0]
	v_pk_fma_f32 v[146:147], v[158:159], s[54:55], v[24:25] op_sel_hi:[1, 0, 0] neg_lo:[0, 0, 1] neg_hi:[0, 0, 1]
	v_add_f32_e32 v24, v0, v1
	v_sub_f32_e32 v95, v0, v1
	v_mov_b32_e32 v17, v7
	v_mov_b32_e32 v0, v16
	v_mov_b32_e32 v1, v181
	v_pk_mul_f32 v[4:5], v[16:17], v[0:1]
	v_mov_b32_e32 v143, v7
	v_mov_b32_e32 v0, v142
	v_pk_mul_f32 v[156:157], v[148:149], v[148:149]
	v_pk_mul_f32 v[158:159], v[146:147], v[146:147]
	v_mov_b32_e32 v19, v2
	v_mov_b32_e32 v180, v18
	v_mov_b32_e32 v145, v2
	v_mov_b32_e32 v2, v144
	v_mov_b32_e32 v3, v181
	v_pk_mul_f32 v[6:7], v[142:143], v[0:1]
	v_pk_fma_f32 v[0:1], v[18:19], v[180:181], v[4:5]
	v_pk_fma_f32 v[6:7], v[144:145], v[2:3], v[6:7]
	v_pk_fma_f32 v[2:3], v[18:19], v[180:181], v[4:5] neg_lo:[0, 0, 1] neg_hi:[0, 0, 1]
	v_pk_fma_f32 v[4:5], v[14:15], v[14:15], v[158:159]
	v_pk_fma_f32 v[8:9], v[12:13], v[12:13], v[156:157]
	v_mul_f32_e32 v5, v24, v24
	v_mul_f32_e32 v9, v95, v95
	v_pk_add_f32 v[4:5], v[4:5], v[8:9]
	v_pk_add_f32 v[8:9], v[0:1], v[6:7]
	v_pk_mul_f32 v[6:7], v[0:1], v[6:7]
	v_pk_mul_f32 v[10:11], v[2:3], v[2:3]
	v_mov_b32_e32 v9, v7
	v_pk_add_f32 v[6:7], v[160:161], v[162:163]
	v_xor_b32_e32 v2, 16, v232
	v_mov_b32_e32 v7, v11
	v_pk_add_f32 v[6:7], v[8:9], v[6:7]
	v_lshl_add_u64 v[10:11], s[0:1], 0, v[62:63]
	v_pk_add_f32 v[4:5], v[6:7], v[4:5]
	v_lshlrev_b64 v[10:11], 11, v[10:11]
	v_add_f32_e32 v0, v4, v5
	v_and_b32_e32 v4, 64, v232
	v_add_u32_e32 v4, 64, v4
	v_cmp_lt_i32_e32 vcc, v2, v4
	s_nop 1
	v_cndmask_b32_e32 v2, v232, v2, vcc
	v_lshlrev_b32_e32 v2, 2, v2
	ds_bpermute_b32 v2, v2, v0
	s_waitcnt lgkmcnt(0)
	v_add_f32_e32 v0, v0, v2
	v_xor_b32_e32 v2, 32, v232
	v_cmp_lt_i32_e32 vcc, v2, v4
	s_nop 1
	v_cndmask_b32_e32 v2, v232, v2, vcc
	v_lshlrev_b32_e32 v2, 2, v2
	ds_bpermute_b32 v2, v2, v0
	s_waitcnt lgkmcnt(0)
	v_add_f32_e32 v0, v0, v2
	v_fmamk_f32 v0, v0, 0x3b800000, v178
	v_mul_f32_e32 v2, 0x4b800000, v0
	v_cmp_gt_f32_e32 vcc, s29, v0
	s_nop 1
	v_cndmask_b32_e32 v0, v0, v2, vcc
	v_rsq_f32_e32 v0, v0
	s_nop 0
	v_mul_f32_e32 v2, 0x45800000, v0
	v_cndmask_b32_e32 v2, v0, v2, vcc
	v_mul_f32_e32 v0, v132, v2
	v_mul_f32_e32 v4, v130, v2
	s_waitcnt vmcnt(0)
	v_mul_f32_e32 v0, v182, v0
	s_waitcnt vmcnt(0)
	v_mul_f32_e32 v4, v183, v4
	v_cvt_pk_bf16_f32 v4, v0, v4
	v_mul_f32_e32 v6, v120, v2
	v_mul_f32_e32 v7, v88, v2
	v_mul_f32_e32 v8, v82, v2
	v_mul_f32_e32 v1, v1, v2
	s_waitcnt vmcnt(0)
	v_mul_f32_e32 v0, v184, v6
	v_mul_f32_e32 v6, v118, v2
	s_waitcnt vmcnt(0)
	v_mul_f32_e32 v5, v185, v6
	v_cvt_pk_bf16_f32 v5, v0, v5
	ds_write_b64 v152, v[4:5]
	v_mul_f32_e32 v4, v104, v2
	s_waitcnt vmcnt(0)
	v_mul_f32_e32 v0, v186, v4
	v_mul_f32_e32 v4, v105, v2
	s_waitcnt vmcnt(0)
	v_mul_f32_e32 v4, v187, v4
	v_cvt_pk_bf16_f32 v4, v0, v4
	v_mul_f32_e32 v6, v90, v2
	s_waitcnt vmcnt(0)
	v_mul_f32_e32 v0, v188, v6
	s_waitcnt vmcnt(0)
	v_mul_f32_e32 v5, v189, v7
	v_cvt_pk_bf16_f32 v5, v0, v5
	v_mul_f32_e32 v7, v80, v2
	ds_write_b64 v152, v[4:5] offset:32
	s_waitcnt vmcnt(0)
	v_mul_f32_e32 v0, v7, v190
	s_waitcnt vmcnt(0)
	v_mul_f32_e32 v4, v8, v191
	v_cvt_pk_bf16_f32 v4, v0, v4
	v_mul_f32_e32 v6, v76, v2
	v_mul_f32_e32 v7, v78, v2
	v_mul_f32_e32 v8, v83, v2
	v_lshl_add_u64 v[82:83], v[74:75], 0, v[10:11]
	s_waitcnt vmcnt(0)
	v_mul_f32_e32 v0, v6, v192
	s_waitcnt vmcnt(0)
; __device__ __forceinline__ unsigned cvt_pk_bf16(float lo, float hi) { unsigned r; asm volatile("v_cvt_pk_bf16_f32 %0, %1, %2" : "=v"(r) : "v"(lo), "v"(hi)); return r; }
; #define LAS __attribute__((address_space(3)))
; __host__ __device__ __forceinline__ int fsig(int p) { return (p & 1) ? ((p == 1) ? 32 : 64 - (p >> 1)) : (p >> 1); }
; __device__ __forceinline__ void fourier_stage2(LAS unsigned char* lds, int wave, const bf16* Tp, bf16* MIX, const float* gmix, int gw, int NGW, int lane) {
;     ...
;         for (int t = 0; t < 16; ++t) { const float* gb = gmix + 768 + (t >> 2) * 64; const int p = 16 * (t & 3) + 4 * kq;
;             v2u w; w.x = cvt_pk_bf16(y[t][0] * rn * gb[fsig(p)], y[t][1] * rn * gb[fsig(p + 1)]); w.y = cvt_pk_bf16(y[t][2] * rn * gb[fsig(p + 2)], y[t][3] * rn * gb[fsig(p + 3)]);
;             *(LAS v2u*)(slab + k2 * 264 + 16 * t + 4 * kq) = w; }
	v_mul_f32_e32 v5, v7, v193
	v_cvt_pk_bf16_f32 v5, v0, v5
	v_mul_f32_e32 v7, v79, v2
	ds_write_b64 v152, v[4:5] offset:64
	s_waitcnt vmcnt(0)
	v_mul_f32_e32 v0, v7, v194
	s_waitcnt vmcnt(0)
	v_mul_f32_e32 v4, v8, v195
	v_cvt_pk_bf16_f32 v4, v0, v4
	v_mul_f32_e32 v6, v85, v2
	v_mul_f32_e32 v7, v87, v2
	v_mul_f32_e32 v8, v86, v2
	s_waitcnt vmcnt(0)
	v_mul_f32_e32 v0, v6, v196
	s_waitcnt vmcnt(0)
	v_mul_f32_e32 v5, v7, v197
	v_cvt_pk_bf16_f32 v5, v0, v5
	v_mul_f32_e32 v7, v84, v2
	ds_write_b64 v152, v[4:5] offset:96
	s_waitcnt vmcnt(0)
	v_mul_f32_e32 v0, v7, v198
	s_waitcnt vmcnt(0)
	v_mul_f32_e32 v4, v8, v199
	v_cvt_pk_bf16_f32 v4, v0, v4
	v_mul_f32_e32 v6, v102, v2
	v_mul_f32_e32 v7, v100, v2
	v_mul_f32_e32 v8, v114, v2
	s_waitcnt vmcnt(0)
	v_mul_f32_e32 v0, v6, v200
	s_waitcnt vmcnt(0)
	v_mul_f32_e32 v5, v7, v201
	v_cvt_pk_bf16_f32 v5, v0, v5
	v_mul_f32_e32 v7, v116, v2
	ds_write_b64 v152, v[4:5] offset:128
	s_waitcnt vmcnt(0)
	v_mul_f32_e32 v0, v7, v202
	s_waitcnt vmcnt(0)
	v_mul_f32_e32 v4, v8, v203
	v_cvt_pk_bf16_f32 v4, v0, v4
	v_mul_f32_e32 v6, v112, v2
	v_mul_f32_e32 v7, v110, v2
	v_mul_f32_e32 v8, v98, v2
	s_waitcnt vmcnt(0)
	v_mul_f32_e32 v0, v6, v204
	s_waitcnt vmcnt(0)
	v_mul_f32_e32 v5, v7, v205
	v_cvt_pk_bf16_f32 v5, v0, v5
	v_mul_f32_e32 v7, v96, v2
	ds_write_b64 v152, v[4:5] offset:160
	s_waitcnt vmcnt(0)
	v_mul_f32_e32 v0, v7, v206
	s_waitcnt vmcnt(0)
	v_mul_f32_e32 v4, v8, v207
	v_cvt_pk_bf16_f32 v4, v0, v4
	v_mul_f32_e32 v6, v92, v2
	v_mul_f32_e32 v7, v94, v2
	v_mul_f32_e32 v8, v81, v2
	s_waitcnt vmcnt(0)
	v_mul_f32_e32 v0, v6, v208
	s_waitcnt vmcnt(0)
	v_mul_f32_e32 v5, v7, v209
	v_cvt_pk_bf16_f32 v5, v0, v5
	v_mul_f32_e32 v7, v77, v2
	ds_write_b64 v152, v[4:5] offset:192
	s_waitcnt vmcnt(0)
	v_mul_f32_e32 v0, v7, v210
	s_waitcnt vmcnt(0)
	v_mul_f32_e32 v4, v8, v211
	v_cvt_pk_bf16_f32 v4, v0, v4
	v_mul_f32_e32 v6, v107, v2
	v_mul_f32_e32 v7, v109, v2
	v_mul_f32_e32 v8, v93, v2
	s_waitcnt vmcnt(0)
	v_mul_f32_e32 v0, v6, v212
	s_waitcnt vmcnt(0)
	v_mul_f32_e32 v5, v7, v213
	v_cvt_pk_bf16_f32 v5, v0, v5
	v_mul_f32_e32 v7, v91, v2
	ds_write_b64 v152, v[4:5] offset:224
	s_waitcnt vmcnt(0)
	v_mul_f32_e32 v0, v7, v214
	s_waitcnt vmcnt(0)
	v_mul_f32_e32 v4, v8, v215
	v_cvt_pk_bf16_f32 v4, v0, v4
	v_mul_f32_e32 v6, v128, v2
	v_mul_f32_e32 v7, v126, v2
	v_mul_f32_e32 v8, v138, v2
	s_waitcnt vmcnt(0)
	v_mul_f32_e32 v0, v6, v216
	s_waitcnt vmcnt(0)
	v_mul_f32_e32 v5, v7, v217
	v_cvt_pk_bf16_f32 v5, v0, v5
	v_mul_f32_e32 v7, v140, v2
	ds_write_b64 v152, v[4:5] offset:256
	s_waitcnt vmcnt(0)
	v_mul_f32_e32 v0, v7, v218
	s_waitcnt vmcnt(0)
	v_mul_f32_e32 v4, v8, v219
	v_cvt_pk_bf16_f32 v4, v0, v4
	v_mul_f32_e32 v6, v136, v2
	v_mul_f32_e32 v7, v134, v2
	v_mul_f32_e32 v8, v124, v2
	s_waitcnt vmcnt(0)
	v_mul_f32_e32 v0, v6, v220
	s_waitcnt vmcnt(0)
	v_mul_f32_e32 v5, v7, v221
	v_cvt_pk_bf16_f32 v5, v0, v5
	v_mul_f32_e32 v7, v122, v2
	ds_write_b64 v152, v[4:5] offset:288
	s_waitcnt vmcnt(0)
	v_mul_f32_e32 v0, v7, v164
	s_waitcnt vmcnt(0)
	v_mul_f32_e32 v4, v8, v165
	v_cvt_pk_bf16_f32 v4, v0, v4
	v_mul_f32_e32 v6, v28, v2
	v_mul_f32_e32 v7, v30, v2
	v_mul_f32_e32 v8, v89, v2
	s_waitcnt vmcnt(0)
	v_mul_f32_e32 v0, v6, v166
	s_waitcnt vmcnt(0)
	v_mul_f32_e32 v5, v7, v167
	v_cvt_pk_bf16_f32 v5, v0, v5
	v_mul_f32_e32 v7, v31, v2
	ds_write_b64 v152, v[4:5] offset:320
	s_waitcnt vmcnt(0)
	v_mul_f32_e32 v0, v7, v168
	s_waitcnt vmcnt(0)
	v_mul_f32_e32 v4, v8, v169
	v_cvt_pk_bf16_f32 v4, v0, v4
	v_mul_f32_e32 v6, v25, v2
	v_mul_f32_e32 v7, v27, v2
	v_mul_f32_e32 v8, v29, v2
	s_waitcnt vmcnt(0)
	v_mul_f32_e32 v0, v6, v170
	s_waitcnt vmcnt(0)
; __device__ __forceinline__ unsigned cvt_pk_bf16(float lo, float hi) { unsigned r; asm volatile("v_cvt_pk_bf16_f32 %0, %1, %2" : "=v"(r) : "v"(lo), "v"(hi)); return r; }
; #define LAS __attribute__((address_space(3)))
; #define LDS_WAIT() asm volatile("s_waitcnt lgkmcnt(0)" ::: "memory")
; __host__ __device__ __forceinline__ int fsig(int p) { return (p & 1) ? ((p == 1) ? 32 : 64 - (p >> 1)) : (p >> 1); }
; __device__ __forceinline__ void fourier_stage2(LAS unsigned char* lds, int wave, const bf16* Tp, bf16* MIX, const float* gmix, int gw, int NGW, int lane) {
;     ...
;         for (int t = 0; t < 16; ++t) { const float* gb = gmix + 768 + (t >> 2) * 64; const int p = 16 * (t & 3) + 4 * kq;
;             v2u w; w.x = cvt_pk_bf16(y[t][0] * rn * gb[fsig(p)], y[t][1] * rn * gb[fsig(p + 1)]); w.y = cvt_pk_bf16(y[t][2] * rn * gb[fsig(p + 2)], y[t][3] * rn * gb[fsig(p + 3)]);
;             *(LAS v2u*)(slab + k2 * 264 + 16 * t + 4 * kq) = w; }
;         LDS_WAIT();
; #pragma unroll
;         for (int it = 0; it < 8; ++it) { const int r = it * 2 + (lane >> 5), ch = lane & 31; const v4u v = *(const LAS v4u*)(slab + r * 264 + ch * 8);
;             *(v4u*)(MIX + ((size_t)b * SEQ + k1 + 512 * r) * 1024 + 768 + ch * 8) = v; }
	v_mul_f32_e32 v5, v7, v171
	v_cvt_pk_bf16_f32 v5, v0, v5
	v_mul_f32_e32 v7, v26, v2
	ds_write_b64 v152, v[4:5] offset:352
	s_waitcnt vmcnt(0)
	v_mul_f32_e32 v0, v7, v172
	s_waitcnt vmcnt(0)
	v_mul_f32_e32 v4, v8, v173
	v_cvt_pk_bf16_f32 v4, v0, v4
	v_mul_f32_e32 v6, v22, v2
	v_mul_f32_e32 v7, v20, v2
	v_mul_f32_e32 v8, v142, v2
	v_add_u32_e32 v22, v153, v154
	s_waitcnt vmcnt(0)
	v_mul_f32_e32 v0, v6, v174
	s_waitcnt vmcnt(0)
	v_mul_f32_e32 v5, v7, v175
	v_cvt_pk_bf16_f32 v5, v0, v5
	v_mul_f32_e32 v7, v144, v2
	ds_write_b64 v152, v[4:5] offset:384
	s_waitcnt vmcnt(0)
	v_mul_f32_e32 v0, v7, v222
	s_waitcnt vmcnt(0)
	v_mul_f32_e32 v4, v8, v223
	v_cvt_pk_bf16_f32 v4, v0, v4
	v_mul_f32_e32 v6, v18, v2
	v_mul_f32_e32 v7, v16, v2
	v_mul_f32_e32 v8, v148, v2
	v_lshl_add_u64 v[16:17], s[0:1], 0, v[68:69]
	v_lshl_add_u64 v[18:19], s[0:1], 0, v[70:71]
	v_lshlrev_b64 v[16:17], 11, v[16:17]
	v_lshlrev_b64 v[18:19], 11, v[18:19]
	v_lshl_add_u64 v[88:89], v[74:75], 0, v[16:17]
	v_lshl_add_u64 v[90:91], v[74:75], 0, v[18:19]
	s_waitcnt vmcnt(0)
	v_mul_f32_e32 v0, v6, v224
	s_waitcnt vmcnt(0)
	v_mul_f32_e32 v5, v7, v225
	v_cvt_pk_bf16_f32 v5, v0, v5
	v_mul_f32_e32 v7, v12, v2
	ds_write_b64 v152, v[4:5] offset:416
	v_lshl_add_u64 v[12:13], s[0:1], 0, v[64:65]
	v_lshlrev_b64 v[12:13], 11, v[12:13]
	v_lshl_add_u64 v[84:85], v[74:75], 0, v[12:13]
	s_waitcnt vmcnt(0)
	v_mul_f32_e32 v0, v7, v226
	s_waitcnt vmcnt(0)
	v_mul_f32_e32 v4, v8, v227
	v_cvt_pk_bf16_f32 v4, v0, v4
	v_mul_f32_e32 v6, v14, v2
	v_mul_f32_e32 v7, v146, v2
	v_mul_f32_e32 v8, v95, v2
	v_lshl_add_u64 v[14:15], s[0:1], 0, v[66:67]
	v_lshlrev_b64 v[14:15], 11, v[14:15]
	v_lshl_add_u64 v[86:87], v[74:75], 0, v[14:15]
	s_waitcnt vmcnt(0)
	v_mul_f32_e32 v0, v6, v242
	s_waitcnt vmcnt(0)
	v_mul_f32_e32 v5, v7, v243
	v_cvt_pk_bf16_f32 v5, v0, v5
	v_mul_f32_e32 v7, v24, v2
	ds_write_b64 v152, v[4:5] offset:448
	v_mul_f32_e32 v2, v3, v2
	s_waitcnt vmcnt(0)
	v_mul_f32_e32 v0, v7, v244
	s_waitcnt vmcnt(0)
	v_mul_f32_e32 v4, v8, v245
	v_cvt_pk_bf16_f32 v0, v0, v4
	v_lshl_add_u64 v[4:5], s[0:1], 0, v[56:57]
	v_lshl_add_u64 v[6:7], s[0:1], 0, v[58:59]
	v_lshl_add_u64 v[8:9], s[0:1], 0, v[60:61]
	v_lshlrev_b64 v[4:5], 11, v[4:5]
	v_lshlrev_b64 v[6:7], 11, v[6:7]
	v_lshlrev_b64 v[8:9], 11, v[8:9]
	v_lshl_add_u64 v[76:77], v[74:75], 0, v[4:5]
	v_lshl_add_u64 v[78:79], v[74:75], 0, v[6:7]
	v_lshl_add_u64 v[80:81], v[74:75], 0, v[8:9]
	s_waitcnt vmcnt(0)
	v_mul_f32_e32 v1, v1, v246
	s_waitcnt vmcnt(0)
	v_mul_f32_e32 v2, v2, v247
	v_cvt_pk_bf16_f32 v1, v1, v2
	ds_write_b64 v152, v[0:1] offset:480
	s_waitcnt lgkmcnt(0)
	ds_read_b128 v[0:3], v22
	ds_read_b128 v[4:7], v155
	ds_read_b128 v[8:11], v155 offset:1056
	ds_read_b128 v[12:15], v155 offset:2112
	ds_read_b128 v[16:19], v155 offset:3168
	ds_read_b128 v[20:23], v155 offset:4224
	ds_read_b128 v[24:27], v155 offset:5280
	ds_read_b128 v[28:31], v155 offset:6336
	s_waitcnt lgkmcnt(7)
	global_store_dwordx4 v[76:77], v[0:3], off offset:1536
	s_waitcnt lgkmcnt(6)
	global_store_dwordx4 v[78:79], v[4:7], off offset:1536
	s_waitcnt lgkmcnt(5)
	global_store_dwordx4 v[80:81], v[8:11], off offset:1536
	s_waitcnt lgkmcnt(4)
	global_store_dwordx4 v[82:83], v[12:15], off offset:1536
	s_waitcnt lgkmcnt(3)
	global_store_dwordx4 v[84:85], v[16:19], off offset:1536
	s_waitcnt lgkmcnt(2)
	global_store_dwordx4 v[86:87], v[20:23], off offset:1536
	s_waitcnt lgkmcnt(1)
	global_store_dwordx4 v[88:89], v[24:27], off offset:1536
	s_waitcnt lgkmcnt(0)
	global_store_dwordx4 v[90:91], v[28:31], off offset:1536
	s_waitcnt lgkmcnt(0)
	s_cbranch_scc0 .LBB0_501

;     ...
;     f32x4 x[NR][4];
; #pragma unroll
;     for (int r = 0; r < NR; ++r)
; #pragma unroll
;         for (int j = 0; j < 4; ++j) x[r][j] = *(const f32x4*)(xin + (size_t)r * DM + j * 256 + lane * 4);
;     if (upd) {
;         f32x4 y[NR][4];
; #pragma unroll
;         for (int r = 0; r < NR; ++r)
; #pragma unroll
;             for (int j = 0; j < 4; ++j) {
;                 if (NP == 0) { const v2u w = *(const v2u*)(upd + (size_t)r * DM + j * 256 + lane * 4); y[r][j][0] = bflo(w.x); y[r][j][1] = bfhi(w.x); y[r][j][2] = bflo(w.y); y[r][j][3] = bfhi(w.y); }
;                 else { const float* pp = (const float*)upd + (size_t)r * DM + j * 256 + lane * 4; f32x4 t = *(const f32x4*)pp;
; #pragma unroll
;                     for (int p = 1; p < NP; ++p) t = t + *(const f32x4*)(pp + (size_t)p * 2048 * 1024);
;                     y[r][j] = t; } }
;         float rr[NR];
; #pragma unroll
;         for (int r = 0; r < NR; ++r) { float ss = 0.f;
; #pragma unroll
;             for (int j = 0; j < 4; ++j) ss += (y[r][j][0] * y[r][j][0] + y[r][j][1] * y[r][j][1]) + (y[r][j][2] * y[r][j][2] + y[r][j][3] * y[r][j][3]);
;             rr[r] = ss; }
; #pragma unroll
;         for (int r = 0; r < NR; ++r) rr[r] = rsqrtf(wave_sum(rr[r]) * (1.f / 1024.f) + EPSN);
.LBB0_656:
	s_ashr_i32 s67, s66, 31
	s_lshl_b64 s[4:5], s[66:67], 12
	s_add_u32 s6, s20, s4
	v_mov_b32_e32 v0, v228
	s_addc_u32 s7, s21, s5
	s_add_u32 s4, s59, s4
	v_lshlrev_b32_e32 v18, 2, v0
	v_ashrrev_i32_e32 v19, 31, v18
	s_addc_u32 s5, s18, s5
	v_lshlrev_b64 v[20:21], 2, v[18:19]
	v_lshl_add_u64 v[36:37], s[4:5], 0, v[20:21]
	v_add_co_u32_e32 v38, vcc, s29, v36
	v_lshl_add_u64 v[0:1], s[6:7], 0, v[20:21]
	s_nop 0
	v_addc_co_u32_e32 v39, vcc, 0, v37, vcc
	s_nop 0
	v_add_co_u32_e32 v40, vcc, s19, v36
	v_addc_co_u32_e32 v41, vcc, 0, v37, vcc
	v_add_co_u32_e32 v42, vcc, s22, v36
	v_lshl_add_u64 v[46:47], s[0:1], 0, v[20:21]
	s_nop 0
	v_addc_co_u32_e32 v43, vcc, 0, v37, vcc
	v_lshl_add_u64 v[48:49], s[12:13], 0, v[20:21]
	s_add_u32 s4, s60, s64
	s_addc_u32 s5, s61, s65
	global_load_dwordx4 v[56:59], v[0:1], off
	global_load_dwordx4 v[60:63], v[0:1], off offset:1024
	global_load_dwordx4 v[64:67], v[0:1], off offset:2048
	global_load_dwordx4 v[68:71], v[0:1], off offset:3072
	global_load_dwordx4 v[72:75], v[36:37], off
	global_load_dwordx4 v[76:79], v[38:39], off
	global_load_dwordx4 v[80:83], v[40:41], off
	global_load_dwordx4 v[84:87], v[42:43], off
	global_load_dwordx4 v[88:91], v[36:37], off offset:1024
	global_load_dwordx4 v[92:95], v[38:39], off offset:1024
	global_load_dwordx4 v[96:99], v[40:41], off offset:1024
	global_load_dwordx4 v[100:103], v[42:43], off offset:1024
	global_load_dwordx4 v[104:107], v[36:37], off offset:2048
	global_load_dwordx4 v[108:111], v[38:39], off offset:2048
	global_load_dwordx4 v[112:115], v[40:41], off offset:2048
	global_load_dwordx4 v[116:119], v[42:43], off offset:2048
	global_load_dwordx4 v[120:123], v[36:37], off offset:3072
	global_load_dwordx4 v[124:127], v[38:39], off offset:3072
	global_load_dwordx4 v[128:131], v[40:41], off offset:3072
	global_load_dwordx4 v[132:135], v[42:43], off offset:3072
	global_load_dwordx4 v[136:139], v[46:47], off
	global_load_dwordx4 v[140:143], v[48:49], off
	global_load_dwordx4 v[144:147], v[46:47], off offset:1024
	global_load_dwordx4 v[148:151], v[48:49], off offset:1024
	global_load_dwordx4 v[152:155], v[46:47], off offset:2048
	global_load_dwordx4 v[156:159], v[48:49], off offset:2048
	global_load_dwordx4 v[160:163], v[46:47], off offset:3072
	s_waitcnt vmcnt(0)
	v_pk_add_f32 v[16:17], v[74:75], v[78:79]
	v_pk_add_f32 v[26:27], v[72:73], v[76:77]
	s_waitcnt vmcnt(0)
	v_pk_add_f32 v[16:17], v[16:17], v[82:83]
	v_pk_add_f32 v[26:27], v[26:27], v[80:81]
	s_waitcnt vmcnt(0)
	v_pk_add_f32 v[16:17], v[16:17], v[86:87]
	v_pk_add_f32 v[22:23], v[26:27], v[84:85]
	s_waitcnt vmcnt(0)
	v_pk_add_f32 v[30:31], v[90:91], v[94:95]
	v_pk_add_f32 v[28:29], v[88:89], v[92:93]
	s_waitcnt vmcnt(0)
	v_pk_add_f32 v[30:31], v[30:31], v[98:99]
	v_pk_add_f32 v[32:33], v[28:29], v[96:97]
	s_waitcnt vmcnt(0)
	v_pk_add_f32 v[24:25], v[30:31], v[102:103]
	v_pk_add_f32 v[26:27], v[32:33], v[100:101]
	s_waitcnt vmcnt(0)
	v_pk_add_f32 v[34:35], v[106:107], v[110:111]
	v_pk_add_f32 v[32:33], v[104:105], v[108:109]
	s_waitcnt vmcnt(0)
	v_pk_add_f32 v[34:35], v[34:35], v[114:115]
	v_pk_add_f32 v[44:45], v[32:33], v[112:113]
	s_waitcnt vmcnt(0)
	v_pk_add_f32 v[28:29], v[34:35], v[118:119]
	s_nop 0
	v_pk_add_f32 v[30:31], v[44:45], v[116:117]
	s_waitcnt vmcnt(0)
	v_pk_add_f32 v[38:39], v[122:123], v[126:127]
	v_pk_add_f32 v[36:37], v[120:121], v[124:125]
	s_waitcnt vmcnt(0)
	v_pk_add_f32 v[38:39], v[38:39], v[130:131]
	v_pk_add_f32 v[40:41], v[36:37], v[128:129]
	s_waitcnt vmcnt(0)
	v_pk_add_f32 v[32:33], v[38:39], v[134:135]
	v_pk_mul_f32 v[36:37], v[16:17], v[16:17]
	v_pk_mul_f32 v[38:39], v[22:23], v[22:23]
	v_pk_add_f32 v[34:35], v[40:41], v[132:133]
	v_pk_mov_b32 v[40:41], v[38:39], v[36:37] op_sel:[1, 0]
	v_mov_b32_e32 v39, v37
	v_pk_add_f32 v[36:37], v[40:41], v[38:39]
	v_pk_mul_f32 v[38:39], v[24:25], v[24:25]
	v_pk_mul_f32 v[40:41], v[26:27], v[26:27]
	v_pk_add_f32 v[36:37], v[36:37], v[36:37] op_sel:[0, 1] op_sel_hi:[1, 0]
	v_pk_mov_b32 v[42:43], v[40:41], v[38:39] op_sel:[1, 0]
	v_mov_b32_e32 v41, v39
	v_pk_add_f32 v[38:39], v[42:43], v[40:41]
	v_mul_f32_e32 v40, v34, v34
	v_mul_f32_e32 v41, v35, v35
	v_pk_add_f32 v[38:39], v[38:39], v[38:39] op_sel:[0, 1] op_sel_hi:[1, 0]
	v_mov_b32_e32 v37, v40
	v_mov_b32_e32 v39, v41
	v_pk_add_f32 v[36:37], v[36:37], v[38:39]
	v_mul_f32_e32 v38, v31, v31
	v_mul_f32_e32 v40, v29, v29
	v_mul_f32_e32 v42, v32, v32
	v_mul_f32_e32 v43, v33, v33
	v_pk_fma_f32 v[38:39], v[30:31], v[30:31], v[38:39] op_sel_hi:[1, 1, 0]
	v_pk_fma_f32 v[40:41], v[28:29], v[28:29], v[40:41] op_sel_hi:[1, 1, 0]
	v_mov_b32_e32 v39, v42
	v_mov_b32_e32 v41, v43
	v_pk_add_f32 v[38:39], v[38:39], v[40:41]
	s_nop 0
	v_pk_add_f32 v[36:37], v[36:37], v[38:39]
	v_xor_b32_e32 v38, 1, v232
	v_add_f32_e32 v36, v36, v37
	v_and_b32_e32 v37, 64, v232
	v_add_u32_e32 v37, 64, v37
	v_cmp_lt_i32_e32 vcc, v38, v37
	s_nop 1
	v_cndmask_b32_e32 v38, v232, v38, vcc
	v_lshlrev_b32_e32 v45, 2, v38
	v_xor_b32_e32 v38, 2, v232
	v_cmp_lt_i32_e32 vcc, v38, v37
	s_nop 1
	v_cndmask_b32_e32 v38, v232, v38, vcc
	v_lshlrev_b32_e32 v50, 2, v38
	v_xor_b32_e32 v38, 4, v232
	v_cmp_lt_i32_e32 vcc, v38, v37
	s_nop 1
	v_cndmask_b32_e32 v38, v232, v38, vcc
	v_lshlrev_b32_e32 v51, 2, v38
	v_xor_b32_e32 v38, 8, v232
	v_cmp_lt_i32_e32 vcc, v38, v37
	s_nop 1
	v_cndmask_b32_e32 v38, v232, v38, vcc
	v_lshlrev_b32_e32 v52, 2, v38
	v_xor_b32_e32 v38, 16, v232
	v_cmp_lt_i32_e32 vcc, v38, v37
	s_nop 1
	v_cndmask_b32_e32 v38, v232, v38, vcc
	v_lshlrev_b32_e32 v53, 2, v38
	v_xor_b32_e32 v38, 32, v232
	v_cmp_lt_i32_e32 vcc, v38, v37
	s_nop 1
	v_cndmask_b32_e32 v37, v232, v38, vcc
	v_lshlrev_b32_e32 v54, 2, v37
	ds_bpermute_b32 v37, v45, v36
	s_waitcnt lgkmcnt(0)
;     ...
;         for (int r = 0; r < NR; ++r) rr[r] = rsqrtf(wave_sum(rr[r]) * (1.f / 1024.f) + EPSN);
; #pragma unroll
;         for (int j = 0; j < 4; ++j) { const f32x4 g = *(const f32x4*)(gate + j * 256 + lane * 4) * *(const f32x4*)(gupd + j * 256 + lane * 4);
; #pragma unroll
;             for (int r = 0; r < NR; ++r) x[r][j] = x[r][j] + g * (y[r][j] * rr[r]); }
;     }
;     if (upd2) {
;         f32x4 y[NR][4];
; #pragma unroll
;         for (int r = 0; r < NR; ++r)
; #pragma unroll
;             for (int j = 0; j < 4; ++j) { const v2u w = *(const v2u*)(upd2 + (size_t)r * DM + j * 256 + lane * 4); y[r][j][0] = bflo(w.x); y[r][j][1] = bfhi(w.x); y[r][j][2] = bflo(w.y); y[r][j][3] = bfhi(w.y); }
;         float rr[NR];
; #pragma unroll
;         for (int r = 0; r < NR; ++r) { float ss = 0.f;
; #pragma unroll
;             for (int j = 0; j < 4; ++j) ss += (y[r][j][0] * y[r][j][0] + y[r][j][1] * y[r][j][1]) + (y[r][j][2] * y[r][j][2] + y[r][j][3] * y[r][j][3]);
;             rr[r] = ss; }
; #pragma unroll
;         for (int r = 0; r < NR; ++r) rr[r] = rsqrtf(wave_sum(rr[r]) * (1.f / 1024.f) + EPSN);
; #pragma unroll
;         for (int j = 0; j < 4; ++j) { const f32x4 g = *(const f32x4*)(gate2 + j * 256 + lane * 4) * *(const f32x4*)(gupd2 + j * 256 + lane * 4);
; #pragma unroll
;             for (int r = 0; r < NR; ++r) x[r][j] = x[r][j] + g * (y[r][j] * rr[r]); }
;     }
;     if (xout) {
; #pragma unroll
;         for (int r = 0; r < NR; ++r)
; #pragma unroll
;             for (int j = 0; j < 4; ++j) *(f32x4*)(xout + (size_t)r * DM + j * 256 + lane * 4) = x[r][j];
;     }
;     if (hxout) {
;         float rr[NR];
; #pragma unroll
;         for (int r = 0; r < NR; ++r) { float ss = 0.f;
; #pragma unroll
;             for (int j = 0; j < 4; ++j) ss += (x[r][j][0] * x[r][j][0] + x[r][j][1] * x[r][j][1]) + (x[r][j][2] * x[r][j][2] + x[r][j][3] * x[r][j][3]);
;             rr[r] = ss; }
; #pragma unroll
;         for (int r = 0; r < NR; ++r) rr[r] = rsqrtf(wave_sum(rr[r]) * (1.f / 1024.f) + EPSN);
; #pragma unroll
;         for (int j = 0; j < 4; ++j) { const f32x4 g = *(const f32x4*)(gn + j * 256 + lane * 4) * (*(const f32x4*)(sc + j * 256 + lane * 4) + 1.f), s0 = *(const f32x4*)(sh + j * 256 + lane * 4);
	v_add_f32_e32 v36, v36, v37
	ds_bpermute_b32 v37, v50, v36
	s_waitcnt lgkmcnt(0)
	v_add_f32_e32 v36, v36, v37
	ds_bpermute_b32 v37, v51, v36
	s_waitcnt lgkmcnt(0)
	v_add_f32_e32 v36, v36, v37
	ds_bpermute_b32 v37, v52, v36
	s_waitcnt lgkmcnt(0)
	v_add_f32_e32 v36, v36, v37
	ds_bpermute_b32 v37, v53, v36
	s_waitcnt lgkmcnt(0)
	v_add_f32_e32 v36, v36, v37
	ds_bpermute_b32 v37, v54, v36
	s_waitcnt lgkmcnt(0)
	v_add_f32_e32 v36, v36, v37
	v_fmamk_f32 v36, v36, 0x3a800000, v178
	v_cmp_gt_f32_e32 vcc, s29, v36
	v_mul_f32_e32 v37, 0x4b800000, v36
	s_nop 0
	v_cndmask_b32_e32 v36, v36, v37, vcc
	v_rsq_f32_e32 v36, v36
	s_nop 0
	v_mul_f32_e32 v37, 0x45800000, v36
	v_cndmask_b32_e32 v44, v36, v37, vcc
	v_pk_mul_f32 v[22:23], v[22:23], v[44:45] op_sel_hi:[1, 0]
	v_pk_mul_f32 v[16:17], v[16:17], v[44:45] op_sel_hi:[1, 0]
	v_pk_mul_f32 v[26:27], v[26:27], v[44:45] op_sel_hi:[1, 0]
	v_pk_mul_f32 v[24:25], v[24:25], v[44:45] op_sel_hi:[1, 0]
	s_waitcnt vmcnt(0)
	v_pk_mul_f32 v[38:39], v[138:139], v[142:143]
	v_pk_mul_f32 v[36:37], v[136:137], v[140:141]
	v_pk_fma_f32 v[14:15], v[38:39], v[16:17], v[58:59]
	v_pk_fma_f32 v[12:13], v[36:37], v[22:23], v[56:57]
	s_waitcnt vmcnt(0)
	v_pk_mul_f32 v[16:17], v[146:147], v[150:151]
	v_pk_mul_f32 v[22:23], v[144:145], v[148:149]
	v_pk_fma_f32 v[10:11], v[16:17], v[24:25], v[62:63]
	v_pk_fma_f32 v[8:9], v[22:23], v[26:27], v[60:61]
	v_pk_mul_f32 v[26:27], v[28:29], v[44:45] op_sel_hi:[1, 0]
	s_waitcnt vmcnt(0)
	v_pk_mul_f32 v[16:17], v[154:155], v[158:159]
	v_pk_mul_f32 v[22:23], v[152:153], v[156:157]
	v_pk_mul_f32 v[24:25], v[30:31], v[44:45] op_sel_hi:[1, 0]
	v_pk_fma_f32 v[6:7], v[16:17], v[26:27], v[66:67]
	v_pk_fma_f32 v[4:5], v[22:23], v[24:25], v[64:65]
	global_load_dwordx4 v[26:29], v[48:49], off offset:3072
	s_waitcnt vmcnt(0)
	v_pk_mul_f32 v[16:17], v[162:163], v[28:29]
	v_pk_mul_f32 v[22:23], v[160:161], v[26:27]
	v_pk_mul_f32 v[26:27], v[32:33], v[44:45] op_sel_hi:[1, 0]
	v_pk_mul_f32 v[24:25], v[34:35], v[44:45] op_sel_hi:[1, 0]
	v_pk_fma_f32 v[2:3], v[16:17], v[26:27], v[70:71]
	v_lshl_add_u64 v[16:17], s[4:5], 0, v[20:21]
	v_add_co_u32_e32 v16, vcc, s23, v16
	v_pk_fma_f32 v[0:1], v[22:23], v[24:25], v[68:69]
	s_nop 0
	v_addc_co_u32_e32 v17, vcc, 0, v17, vcc
	global_store_dwordx4 v[16:17], v[12:15], off
	global_store_dwordx4 v[16:17], v[8:11], off offset:1024
	global_store_dwordx4 v[16:17], v[4:7], off offset:2048
	global_store_dwordx4 v[16:17], v[0:3], off offset:3072
	v_pk_mul_f32 v[16:17], v[14:15], v[14:15]
	v_pk_mul_f32 v[22:23], v[12:13], v[12:13]
	s_add_u32 s4, s60, s40
	v_pk_mov_b32 v[24:25], v[22:23], v[16:17] op_sel:[1, 0]
	v_mov_b32_e32 v23, v17
	v_pk_add_f32 v[16:17], v[24:25], v[22:23]
	v_pk_mul_f32 v[22:23], v[10:11], v[10:11]
	v_pk_add_f32 v[16:17], v[16:17], v[16:17] op_sel_hi:[0, 1]
	v_pk_mul_f32 v[24:25], v[8:9], v[8:9]
	v_mul_f32_e32 v16, v4, v4
	v_pk_mov_b32 v[26:27], v[24:25], v[22:23] op_sel:[1, 0]
	v_mov_b32_e32 v25, v23
	v_pk_add_f32 v[22:23], v[26:27], v[24:25]
	v_pk_fma_f32 v[24:25], v[4:5], v[4:5], v[16:17] op_sel_hi:[1, 1, 0]
	v_mul_f32_e32 v16, v6, v6
	v_pk_add_f32 v[22:23], v[22:23], v[22:23] op_sel_hi:[0, 1]
	v_pk_fma_f32 v[26:27], v[6:7], v[6:7], v[16:17] op_sel_hi:[1, 1, 0]
	v_mul_f32_e32 v24, v0, v0
	v_mul_f32_e32 v26, v1, v1
	v_mul_f32_e32 v16, v2, v2
	v_mul_f32_e32 v22, v3, v3
	v_pk_add_f32 v[24:25], v[24:25], v[26:27]
	v_pk_add_f32 v[16:17], v[16:17], v[22:23]
	v_lshl_add_u64 v[22:23], s[34:35], 0, v[20:21]
	v_pk_add_f32 v[16:17], v[24:25], v[16:17]
	v_lshl_add_u64 v[24:25], s[26:27], 0, v[20:21]
	global_load_dwordx4 v[26:29], v[24:25], off
	global_load_dwordx4 v[30:33], v[22:23], off
	v_lshl_add_u64 v[20:21], s[36:37], 0, v[20:21]
	v_add_f32_e32 v16, v16, v17
	ds_bpermute_b32 v17, v45, v16
	s_addc_u32 s5, s61, s41
	v_lshl_add_u64 v[18:19], v[18:19], 1, s[4:5]
	s_add_i32 s66, s66, s96
	s_add_i32 s4, s66, 0x10000
	s_waitcnt lgkmcnt(0)
; __device__ __forceinline__ unsigned cvt_pk_bf16(float lo, float hi) { unsigned r; asm volatile("v_cvt_pk_bf16_f32 %0, %1, %2" : "=v"(r) : "v"(lo), "v"(hi)); return r; }
;     ...
;         float rr[NR];
; #pragma unroll
;         for (int r = 0; r < NR; ++r) { float ss = 0.f;
; #pragma unroll
;             for (int j = 0; j < 4; ++j) ss += (x[r][j][0] * x[r][j][0] + x[r][j][1] * x[r][j][1]) + (x[r][j][2] * x[r][j][2] + x[r][j][3] * x[r][j][3]);
;             rr[r] = ss; }
; #pragma unroll
;         for (int r = 0; r < NR; ++r) rr[r] = rsqrtf(wave_sum(rr[r]) * (1.f / 1024.f) + EPSN);
; #pragma unroll
;         for (int j = 0; j < 4; ++j) { const f32x4 g = *(const f32x4*)(gn + j * 256 + lane * 4) * (*(const f32x4*)(sc + j * 256 + lane * 4) + 1.f), s0 = *(const f32x4*)(sh + j * 256 + lane * 4);
; #pragma unroll
;             for (int r = 0; r < NR; ++r) { const f32x4 h = (x[r][j] * rr[r]) * g + s0; v2u w; w.x = cvt_pk_bf16(h[0], h[1]); w.y = cvt_pk_bf16(h[2], h[3]); *(v2u*)(hxout + (size_t)r * DM + j * 256 + lane * 4) = w; } }
	v_add_f32_e32 v16, v16, v17
	ds_bpermute_b32 v17, v50, v16
	s_add_u32 s64, s64, s30
	s_addc_u32 s65, s65, s31
	s_add_u32 s40, s40, s76
	s_addc_u32 s41, s41, s77
	s_waitcnt lgkmcnt(0)
	v_add_f32_e32 v16, v16, v17
	ds_bpermute_b32 v17, v51, v16
	s_cmp_lt_i32 s4, 0x10800
	s_waitcnt lgkmcnt(0)
	v_add_f32_e32 v16, v16, v17
	ds_bpermute_b32 v17, v52, v16
	s_waitcnt lgkmcnt(0)
	v_add_f32_e32 v16, v16, v17
	ds_bpermute_b32 v17, v53, v16
	s_waitcnt lgkmcnt(0)
	v_add_f32_e32 v16, v16, v17
	ds_bpermute_b32 v17, v54, v16
	s_waitcnt lgkmcnt(0)
	v_add_f32_e32 v16, v16, v17
	v_fmamk_f32 v16, v16, 0x3a800000, v178
	v_cmp_gt_f32_e32 vcc, s29, v16
	v_mul_f32_e32 v17, 0x4b800000, v16
	s_waitcnt vmcnt(0)
	v_pk_add_f32 v[32:33], v[32:33], 1.0 op_sel_hi:[1, 0]
	v_pk_add_f32 v[30:31], v[30:31], 1.0 op_sel_hi:[1, 0]
	v_pk_mul_f32 v[32:33], v[28:29], v[32:33]
	v_pk_mul_f32 v[30:31], v[26:27], v[30:31]
	global_load_dwordx4 v[26:29], v[20:21], off
	v_cndmask_b32_e32 v16, v16, v17, vcc
	v_rsq_f32_e32 v16, v16
	s_nop 0
	v_mul_f32_e32 v17, 0x45800000, v16
	v_cndmask_b32_e32 v16, v16, v17, vcc
	v_pk_mul_f32 v[12:13], v[12:13], v[16:17] op_sel_hi:[1, 0]
	v_pk_mul_f32 v[14:15], v[14:15], v[16:17] op_sel_hi:[1, 0]
	v_pk_mul_f32 v[8:9], v[8:9], v[16:17] op_sel_hi:[1, 0]
	v_pk_mul_f32 v[10:11], v[10:11], v[16:17] op_sel_hi:[1, 0]
	v_pk_mul_f32 v[4:5], v[4:5], v[16:17] op_sel_hi:[1, 0]
	v_pk_mul_f32 v[6:7], v[6:7], v[16:17] op_sel_hi:[1, 0]
	v_pk_mul_f32 v[0:1], v[0:1], v[16:17] op_sel_hi:[1, 0]
	v_pk_mul_f32 v[2:3], v[2:3], v[16:17] op_sel_hi:[1, 0]
	s_waitcnt vmcnt(0)
	v_pk_fma_f32 v[12:13], v[30:31], v[12:13], v[26:27]
	v_pk_fma_f32 v[28:29], v[32:33], v[14:15], v[28:29]
	v_cvt_pk_bf16_f32 v14, v12, v13
	v_add_co_u32_e32 v12, vcc, s24, v18
	v_cvt_pk_bf16_f32 v15, v28, v29
	s_nop 1
	v_addc_co_u32_e32 v13, vcc, 0, v19, vcc
	global_store_dwordx2 v[12:13], v[14:15], off
	global_load_dwordx4 v[26:29], v[24:25], off offset:1024
	global_load_dwordx4 v[30:33], v[22:23], off offset:1024
	s_waitcnt vmcnt(0)
	v_pk_add_f32 v[14:15], v[32:33], 1.0 op_sel_hi:[1, 0]
	v_pk_add_f32 v[18:19], v[30:31], 1.0 op_sel_hi:[1, 0]
	v_pk_mul_f32 v[14:15], v[28:29], v[14:15]
	v_pk_mul_f32 v[18:19], v[26:27], v[18:19]
	global_load_dwordx4 v[26:29], v[20:21], off offset:1024
	s_waitcnt vmcnt(0)
	v_pk_fma_f32 v[8:9], v[18:19], v[8:9], v[26:27]
	v_pk_fma_f32 v[10:11], v[14:15], v[10:11], v[28:29]
	v_cvt_pk_bf16_f32 v8, v8, v9
	s_nop 0
	v_cvt_pk_bf16_f32 v9, v10, v11
	global_store_dwordx2 v[12:13], v[8:9], off offset:512
	global_load_dwordx4 v[8:11], v[24:25], off offset:2048
	s_nop 0
	global_load_dwordx4 v[26:29], v[22:23], off offset:2048
	s_waitcnt vmcnt(0)
	v_pk_add_f32 v[14:15], v[28:29], 1.0 op_sel_hi:[1, 0]
	v_pk_add_f32 v[18:19], v[26:27], 1.0 op_sel_hi:[1, 0]
	v_pk_mul_f32 v[14:15], v[10:11], v[14:15]
	v_pk_mul_f32 v[18:19], v[8:9], v[18:19]
	global_load_dwordx4 v[8:11], v[20:21], off offset:2048
	s_waitcnt vmcnt(0)
	v_pk_fma_f32 v[4:5], v[18:19], v[4:5], v[8:9]
	v_pk_fma_f32 v[6:7], v[14:15], v[6:7], v[10:11]
	v_cvt_pk_bf16_f32 v4, v4, v5
	s_nop 0
	v_cvt_pk_bf16_f32 v5, v6, v7
	global_store_dwordx2 v[12:13], v[4:5], off offset:1024
	global_load_dwordx4 v[4:7], v[24:25], off offset:3072
	s_nop 0
	global_load_dwordx4 v[8:11], v[22:23], off offset:3072
	s_waitcnt vmcnt(0)
	v_pk_add_f32 v[10:11], v[10:11], 1.0 op_sel_hi:[1, 0]
	v_pk_add_f32 v[8:9], v[8:9], 1.0 op_sel_hi:[1, 0]
	v_pk_mul_f32 v[10:11], v[6:7], v[10:11]
	v_pk_mul_f32 v[8:9], v[4:5], v[8:9]
	global_load_dwordx4 v[4:7], v[20:21], off offset:3072
	s_waitcnt vmcnt(0)
	v_pk_fma_f32 v[0:1], v[0:1], v[8:9], v[4:5]
	v_pk_fma_f32 v[2:3], v[2:3], v[10:11], v[6:7]
	v_cvt_pk_bf16_f32 v0, v0, v1
	s_nop 0
	v_cvt_pk_bf16_f32 v1, v2, v3
	global_store_dwordx2 v[12:13], v[0:1], off offset:1536
	s_cbranch_scc1 .LBB0_656

;     ...
;     f32x4 x[NR][4];
; #pragma unroll
;     for (int r = 0; r < NR; ++r)
; #pragma unroll
;         for (int j = 0; j < 4; ++j) x[r][j] = *(const f32x4*)(xin + (size_t)r * DM + j * 256 + lane * 4);
;     if (upd) {
;         f32x4 y[NR][4];
; #pragma unroll
;         for (int r = 0; r < NR; ++r)
; #pragma unroll
;             for (int j = 0; j < 4; ++j) {
;                 if (NP == 0) { const v2u w = *(const v2u*)(upd + (size_t)r * DM + j * 256 + lane * 4); y[r][j][0] = bflo(w.x); y[r][j][1] = bfhi(w.x); y[r][j][2] = bflo(w.y); y[r][j][3] = bfhi(w.y); }
;                 else { const float* pp = (const float*)upd + (size_t)r * DM + j * 256 + lane * 4; f32x4 t = *(const f32x4*)pp;
; #pragma unroll
;                     for (int p = 1; p < NP; ++p) t = t + *(const f32x4*)(pp + (size_t)p * 2048 * 1024);
;                     y[r][j] = t; } }
;         float rr[NR];
; #pragma unroll
;         for (int r = 0; r < NR; ++r) { float ss = 0.f;
; #pragma unroll
;             for (int j = 0; j < 4; ++j) ss += (y[r][j][0] * y[r][j][0] + y[r][j][1] * y[r][j][1]) + (y[r][j][2] * y[r][j][2] + y[r][j][3] * y[r][j][3]);
;             rr[r] = ss; }
; #pragma unroll
;         for (int r = 0; r < NR; ++r) rr[r] = rsqrtf(wave_sum(rr[r]) * (1.f / 1024.f) + EPSN);
.LBB0_884:
	s_ashr_i32 s11, s10, 31
	s_lshl_b64 s[12:13], s[10:11], 12
	s_add_u32 s12, s59, s12
	v_mov_b32_e32 v0, v228
	s_addc_u32 s13, s16, s13
	s_add_u32 s14, s60, s8
	v_lshlrev_b32_e32 v16, 2, v0
	v_ashrrev_i32_e32 v17, 31, v16
	v_lshlrev_b64 v[18:19], 2, v[16:17]
	s_addc_u32 s15, s61, s9
	v_lshl_add_u64 v[0:1], s[14:15], 0, v[18:19]
	v_add_co_u32_e32 v0, vcc, s27, v0
	v_lshl_add_u64 v[36:37], s[12:13], 0, v[18:19]
	s_nop 0
	v_addc_co_u32_e32 v1, vcc, 0, v1, vcc
	v_add_co_u32_e32 v38, vcc, s29, v36
	s_nop 0
	v_addc_co_u32_e32 v39, vcc, 0, v37, vcc
	v_add_co_u32_e32 v40, vcc, s17, v36
	v_lshl_add_u64 v[46:47], s[0:1], 0, v[18:19]
	s_nop 0
	v_addc_co_u32_e32 v41, vcc, 0, v37, vcc
	v_add_co_u32_e32 v42, vcc, s26, v36
	v_lshl_add_u64 v[48:49], s[4:5], 0, v[18:19]
	s_nop 0
	v_addc_co_u32_e32 v43, vcc, 0, v37, vcc
	s_add_u32 s12, s60, s6
	s_addc_u32 s13, s61, s7
	s_add_i32 s10, s10, s96
	s_add_i32 s11, s10, 0x10000
	s_add_u32 s8, s8, s30
	s_addc_u32 s9, s9, s31
	s_add_u32 s6, s6, s76
	s_addc_u32 s7, s7, s77
	s_cmp_lt_i32 s11, 0x10800
	global_load_dwordx4 v[56:59], v[0:1], off
	global_load_dwordx4 v[60:63], v[0:1], off offset:1024
	global_load_dwordx4 v[64:67], v[0:1], off offset:2048
	global_load_dwordx4 v[68:71], v[0:1], off offset:3072
	global_load_dwordx4 v[72:75], v[36:37], off
	global_load_dwordx4 v[76:79], v[38:39], off
	global_load_dwordx4 v[80:83], v[40:41], off
	global_load_dwordx4 v[84:87], v[42:43], off
	global_load_dwordx4 v[88:91], v[36:37], off offset:1024
	global_load_dwordx4 v[92:95], v[38:39], off offset:1024
	global_load_dwordx4 v[96:99], v[40:41], off offset:1024
	global_load_dwordx4 v[100:103], v[42:43], off offset:1024
	global_load_dwordx4 v[104:107], v[36:37], off offset:2048
	global_load_dwordx4 v[108:111], v[38:39], off offset:2048
	global_load_dwordx4 v[112:115], v[40:41], off offset:2048
	global_load_dwordx4 v[116:119], v[42:43], off offset:2048
	global_load_dwordx4 v[120:123], v[36:37], off offset:3072
	global_load_dwordx4 v[124:127], v[38:39], off offset:3072
	global_load_dwordx4 v[128:131], v[40:41], off offset:3072
	global_load_dwordx4 v[132:135], v[42:43], off offset:3072
	global_load_dwordx4 v[136:139], v[46:47], off
	global_load_dwordx4 v[140:143], v[48:49], off
	global_load_dwordx4 v[144:147], v[46:47], off offset:1024
	global_load_dwordx4 v[148:151], v[48:49], off offset:1024
	global_load_dwordx4 v[152:155], v[46:47], off offset:2048
	global_load_dwordx4 v[156:159], v[48:49], off offset:2048
	global_load_dwordx4 v[160:163], v[46:47], off offset:3072
	global_load_dwordx4 v[164:167], v[48:49], off offset:3072
	s_waitcnt vmcnt(0)
	v_pk_add_f32 v[26:27], v[74:75], v[78:79]
	v_pk_add_f32 v[24:25], v[72:73], v[76:77]
	s_waitcnt vmcnt(0)
	v_pk_add_f32 v[26:27], v[26:27], v[82:83]
	v_pk_add_f32 v[28:29], v[24:25], v[80:81]
	s_waitcnt vmcnt(0)
	v_pk_add_f32 v[20:21], v[26:27], v[86:87]
	v_pk_add_f32 v[22:23], v[28:29], v[84:85]
	s_waitcnt vmcnt(0)
	v_pk_add_f32 v[30:31], v[90:91], v[94:95]
	v_pk_add_f32 v[28:29], v[88:89], v[92:93]
	s_waitcnt vmcnt(0)
	v_pk_add_f32 v[30:31], v[30:31], v[98:99]
	v_pk_add_f32 v[32:33], v[28:29], v[96:97]
	s_waitcnt vmcnt(0)
	v_pk_add_f32 v[24:25], v[30:31], v[102:103]
	v_pk_add_f32 v[26:27], v[32:33], v[100:101]
	s_waitcnt vmcnt(0)
	v_pk_add_f32 v[34:35], v[106:107], v[110:111]
	v_pk_add_f32 v[32:33], v[104:105], v[108:109]
	s_waitcnt vmcnt(0)
	v_pk_add_f32 v[34:35], v[34:35], v[114:115]
	v_pk_add_f32 v[44:45], v[32:33], v[112:113]
	s_waitcnt vmcnt(0)
	v_pk_add_f32 v[28:29], v[34:35], v[118:119]
	s_nop 0
	v_pk_add_f32 v[30:31], v[44:45], v[116:117]
	s_waitcnt vmcnt(0)
	v_pk_add_f32 v[38:39], v[122:123], v[126:127]
	v_pk_add_f32 v[36:37], v[120:121], v[124:125]
	s_waitcnt vmcnt(0)
	v_pk_add_f32 v[38:39], v[38:39], v[130:131]
	v_pk_add_f32 v[40:41], v[36:37], v[128:129]
	s_waitcnt vmcnt(0)
	v_pk_add_f32 v[32:33], v[38:39], v[134:135]
	v_pk_mul_f32 v[36:37], v[20:21], v[20:21]
	v_pk_mul_f32 v[38:39], v[22:23], v[22:23]
	v_pk_add_f32 v[34:35], v[40:41], v[132:133]
	v_pk_mov_b32 v[40:41], v[38:39], v[36:37] op_sel:[1, 0]
	v_mov_b32_e32 v39, v37
	v_pk_add_f32 v[36:37], v[40:41], v[38:39]
	v_pk_mul_f32 v[38:39], v[24:25], v[24:25]
	v_pk_mul_f32 v[40:41], v[26:27], v[26:27]
	v_pk_add_f32 v[36:37], v[36:37], v[36:37] op_sel:[0, 1] op_sel_hi:[1, 0]
	v_pk_mov_b32 v[42:43], v[40:41], v[38:39] op_sel:[1, 0]
	v_mov_b32_e32 v41, v39
	v_pk_add_f32 v[38:39], v[42:43], v[40:41]
	v_mul_f32_e32 v40, v34, v34
	v_mul_f32_e32 v41, v35, v35
	v_pk_add_f32 v[38:39], v[38:39], v[38:39] op_sel:[0, 1] op_sel_hi:[1, 0]
	v_mov_b32_e32 v37, v40
	v_mov_b32_e32 v39, v41
	v_pk_add_f32 v[36:37], v[36:37], v[38:39]
	v_mul_f32_e32 v38, v31, v31
	v_mul_f32_e32 v40, v29, v29
	v_mul_f32_e32 v42, v32, v32
	v_mul_f32_e32 v43, v33, v33
	v_pk_fma_f32 v[38:39], v[30:31], v[30:31], v[38:39] op_sel_hi:[1, 1, 0]
	v_pk_fma_f32 v[40:41], v[28:29], v[28:29], v[40:41] op_sel_hi:[1, 1, 0]
	v_mov_b32_e32 v39, v42
	v_mov_b32_e32 v41, v43
	v_pk_add_f32 v[38:39], v[38:39], v[40:41]
	s_nop 0
	v_pk_add_f32 v[36:37], v[36:37], v[38:39]
	v_xor_b32_e32 v38, 1, v232
	v_add_f32_e32 v36, v36, v37
	v_and_b32_e32 v37, 64, v232
	v_add_u32_e32 v37, 64, v37
	v_cmp_lt_i32_e32 vcc, v38, v37
	s_nop 1
	v_cndmask_b32_e32 v38, v232, v38, vcc
	v_lshlrev_b32_e32 v45, 2, v38
	v_xor_b32_e32 v38, 2, v232
	v_cmp_lt_i32_e32 vcc, v38, v37
	s_nop 1
	v_cndmask_b32_e32 v38, v232, v38, vcc
	v_lshlrev_b32_e32 v50, 2, v38
	v_xor_b32_e32 v38, 4, v232
	v_cmp_lt_i32_e32 vcc, v38, v37
	s_nop 1
	v_cndmask_b32_e32 v38, v232, v38, vcc
	v_lshlrev_b32_e32 v51, 2, v38
	v_xor_b32_e32 v38, 8, v232
	v_cmp_lt_i32_e32 vcc, v38, v37
	s_nop 1
	v_cndmask_b32_e32 v38, v232, v38, vcc
	v_lshlrev_b32_e32 v52, 2, v38
	v_xor_b32_e32 v38, 16, v232
	v_cmp_lt_i32_e32 vcc, v38, v37
	s_nop 1
	v_cndmask_b32_e32 v38, v232, v38, vcc
	v_lshlrev_b32_e32 v53, 2, v38
	v_xor_b32_e32 v38, 32, v232
	v_cmp_lt_i32_e32 vcc, v38, v37
	s_nop 1
	v_cndmask_b32_e32 v37, v232, v38, vcc
	v_lshlrev_b32_e32 v54, 2, v37
	ds_bpermute_b32 v37, v45, v36
	s_waitcnt lgkmcnt(0)
;     ...
;         for (int r = 0; r < NR; ++r) rr[r] = rsqrtf(wave_sum(rr[r]) * (1.f / 1024.f) + EPSN);
; #pragma unroll
;         for (int j = 0; j < 4; ++j) { const f32x4 g = *(const f32x4*)(gate + j * 256 + lane * 4) * *(const f32x4*)(gupd + j * 256 + lane * 4);
; #pragma unroll
;             for (int r = 0; r < NR; ++r) x[r][j] = x[r][j] + g * (y[r][j] * rr[r]); }
;     }
;     if (upd2) {
;         f32x4 y[NR][4];
; #pragma unroll
;         for (int r = 0; r < NR; ++r)
; #pragma unroll
;             for (int j = 0; j < 4; ++j) { const v2u w = *(const v2u*)(upd2 + (size_t)r * DM + j * 256 + lane * 4); y[r][j][0] = bflo(w.x); y[r][j][1] = bfhi(w.x); y[r][j][2] = bflo(w.y); y[r][j][3] = bfhi(w.y); }
;         float rr[NR];
; #pragma unroll
;         for (int r = 0; r < NR; ++r) { float ss = 0.f;
; #pragma unroll
;             for (int j = 0; j < 4; ++j) ss += (y[r][j][0] * y[r][j][0] + y[r][j][1] * y[r][j][1]) + (y[r][j][2] * y[r][j][2] + y[r][j][3] * y[r][j][3]);
;             rr[r] = ss; }
; #pragma unroll
;         for (int r = 0; r < NR; ++r) rr[r] = rsqrtf(wave_sum(rr[r]) * (1.f / 1024.f) + EPSN);
; #pragma unroll
;         for (int j = 0; j < 4; ++j) { const f32x4 g = *(const f32x4*)(gate2 + j * 256 + lane * 4) * *(const f32x4*)(gupd2 + j * 256 + lane * 4);
; #pragma unroll
;             for (int r = 0; r < NR; ++r) x[r][j] = x[r][j] + g * (y[r][j] * rr[r]); }
;     }
;     if (xout) {
; #pragma unroll
;         for (int r = 0; r < NR; ++r)
; #pragma unroll
;             for (int j = 0; j < 4; ++j) *(f32x4*)(xout + (size_t)r * DM + j * 256 + lane * 4) = x[r][j];
;     }
;     if (hxout) {
;         float rr[NR];
; #pragma unroll
;         for (int r = 0; r < NR; ++r) { float ss = 0.f;
; #pragma unroll
;             for (int j = 0; j < 4; ++j) ss += (x[r][j][0] * x[r][j][0] + x[r][j][1] * x[r][j][1]) + (x[r][j][2] * x[r][j][2] + x[r][j][3] * x[r][j][3]);
;             rr[r] = ss; }
; #pragma unroll
;         for (int r = 0; r < NR; ++r) rr[r] = rsqrtf(wave_sum(rr[r]) * (1.f / 1024.f) + EPSN);
; #pragma unroll
;         for (int j = 0; j < 4; ++j) { const f32x4 g = *(const f32x4*)(gn + j * 256 + lane * 4) * (*(const f32x4*)(sc + j * 256 + lane * 4) + 1.f), s0 = *(const f32x4*)(sh + j * 256 + lane * 4);
; #pragma unroll
	v_add_f32_e32 v36, v36, v37
	ds_bpermute_b32 v37, v50, v36
	s_waitcnt lgkmcnt(0)
	v_add_f32_e32 v36, v36, v37
	ds_bpermute_b32 v37, v51, v36
	s_waitcnt lgkmcnt(0)
	v_add_f32_e32 v36, v36, v37
	ds_bpermute_b32 v37, v52, v36
	s_waitcnt lgkmcnt(0)
	v_add_f32_e32 v36, v36, v37
	ds_bpermute_b32 v37, v53, v36
	s_waitcnt lgkmcnt(0)
	v_add_f32_e32 v36, v36, v37
	ds_bpermute_b32 v37, v54, v36
	s_waitcnt lgkmcnt(0)
	v_add_f32_e32 v36, v36, v37
	v_fmamk_f32 v36, v36, 0x3a800000, v178
	v_cmp_gt_f32_e32 vcc, s29, v36
	v_mul_f32_e32 v37, 0x4b800000, v36
	s_nop 0
	v_cndmask_b32_e32 v36, v36, v37, vcc
	v_rsq_f32_e32 v36, v36
	s_nop 0
	v_mul_f32_e32 v37, 0x45800000, v36
	v_cndmask_b32_e32 v44, v36, v37, vcc
	v_pk_mul_f32 v[20:21], v[20:21], v[44:45] op_sel_hi:[1, 0]
	v_pk_mul_f32 v[22:23], v[22:23], v[44:45] op_sel_hi:[1, 0]
	s_waitcnt vmcnt(0)
	v_pk_mul_f32 v[38:39], v[138:139], v[142:143]
	v_pk_mul_f32 v[36:37], v[136:137], v[140:141]
	v_pk_fma_f32 v[38:39], v[38:39], v[20:21], v[58:59]
	v_pk_fma_f32 v[36:37], v[36:37], v[22:23], v[56:57]
	s_waitcnt vmcnt(0)
	v_pk_mul_f32 v[14:15], v[146:147], v[150:151]
	v_pk_mul_f32 v[12:13], v[144:145], v[148:149]
	v_pk_mul_f32 v[20:21], v[24:25], v[44:45] op_sel_hi:[1, 0]
	v_pk_mul_f32 v[22:23], v[26:27], v[44:45] op_sel_hi:[1, 0]
	v_pk_fma_f32 v[10:11], v[14:15], v[20:21], v[62:63]
	v_pk_fma_f32 v[12:13], v[12:13], v[22:23], v[60:61]
	s_waitcnt vmcnt(0)
	v_pk_mul_f32 v[8:9], v[154:155], v[158:159]
	v_pk_mul_f32 v[14:15], v[152:153], v[156:157]
	v_pk_mul_f32 v[20:21], v[30:31], v[44:45] op_sel_hi:[1, 0]
	v_pk_mul_f32 v[22:23], v[28:29], v[44:45] op_sel_hi:[1, 0]
	v_lshl_add_u64 v[28:29], v[16:17], 1, s[12:13]
	v_pk_fma_f32 v[6:7], v[8:9], v[22:23], v[66:67]
	v_pk_fma_f32 v[8:9], v[14:15], v[20:21], v[64:65]
	s_waitcnt vmcnt(0)
	v_pk_mul_f32 v[4:5], v[162:163], v[166:167]
	v_pk_mul_f32 v[14:15], v[160:161], v[164:165]
	v_pk_mul_f32 v[20:21], v[34:35], v[44:45] op_sel_hi:[1, 0]
	v_pk_mul_f32 v[22:23], v[32:33], v[44:45] op_sel_hi:[1, 0]
	v_pk_fma_f32 v[0:1], v[14:15], v[20:21], v[68:69]
	v_pk_fma_f32 v[2:3], v[4:5], v[22:23], v[70:71]
	v_pk_mul_f32 v[4:5], v[38:39], v[38:39]
	v_pk_mul_f32 v[14:15], v[36:37], v[36:37]
	s_nop 0
	v_pk_mov_b32 v[20:21], v[14:15], v[4:5] op_sel:[1, 0]
	v_mov_b32_e32 v15, v5
	v_pk_add_f32 v[4:5], v[20:21], v[14:15]
	v_pk_mul_f32 v[14:15], v[10:11], v[10:11]
	v_pk_add_f32 v[4:5], v[4:5], v[4:5] op_sel_hi:[0, 1]
	v_pk_mul_f32 v[20:21], v[12:13], v[12:13]
	v_mul_f32_e32 v4, v8, v8
	v_pk_mov_b32 v[22:23], v[20:21], v[14:15] op_sel:[1, 0]
	v_mov_b32_e32 v21, v15
	v_pk_add_f32 v[14:15], v[22:23], v[20:21]
	v_pk_fma_f32 v[20:21], v[8:9], v[8:9], v[4:5] op_sel_hi:[1, 1, 0]
	v_mul_f32_e32 v4, v6, v6
	v_pk_add_f32 v[14:15], v[14:15], v[14:15] op_sel_hi:[0, 1]
	v_pk_fma_f32 v[22:23], v[6:7], v[6:7], v[4:5] op_sel_hi:[1, 1, 0]
	v_mul_f32_e32 v20, v0, v0
	v_mul_f32_e32 v22, v1, v1
	v_mul_f32_e32 v4, v2, v2
	v_mul_f32_e32 v14, v3, v3
	v_pk_add_f32 v[20:21], v[20:21], v[22:23]
	v_pk_add_f32 v[4:5], v[4:5], v[14:15]
	v_lshl_add_u64 v[22:23], s[18:19], 0, v[18:19]
	v_pk_add_f32 v[4:5], v[20:21], v[4:5]
	v_lshl_add_u64 v[20:21], s[24:25], 0, v[18:19]
	v_lshl_add_u64 v[14:15], s[22:23], 0, v[18:19]
	global_load_dwordx4 v[16:19], v[22:23], off
	global_load_dwordx4 v[24:27], v[20:21], off
	v_add_f32_e32 v4, v4, v5
	ds_bpermute_b32 v5, v45, v4
	s_waitcnt lgkmcnt(0)
	v_add_f32_e32 v4, v4, v5
	ds_bpermute_b32 v5, v50, v4
	s_waitcnt lgkmcnt(0)
	v_add_f32_e32 v4, v4, v5
	ds_bpermute_b32 v5, v51, v4
	s_waitcnt lgkmcnt(0)
	v_add_f32_e32 v4, v4, v5
	ds_bpermute_b32 v5, v52, v4
	s_waitcnt lgkmcnt(0)
	v_add_f32_e32 v4, v4, v5
	ds_bpermute_b32 v5, v53, v4
	s_waitcnt lgkmcnt(0)
	v_add_f32_e32 v4, v4, v5
	ds_bpermute_b32 v5, v54, v4
	s_waitcnt lgkmcnt(0)
	v_add_f32_e32 v4, v4, v5
	v_fmamk_f32 v4, v4, 0x3a800000, v178
	v_cmp_gt_f32_e32 vcc, s29, v4
	v_mul_f32_e32 v5, 0x4b800000, v4
	s_waitcnt vmcnt(0)
	v_pk_add_f32 v[26:27], v[26:27], 1.0 op_sel_hi:[1, 0]
	v_pk_add_f32 v[24:25], v[24:25], 1.0 op_sel_hi:[1, 0]
	v_pk_mul_f32 v[26:27], v[18:19], v[26:27]
	v_pk_mul_f32 v[24:25], v[16:17], v[24:25]
	global_load_dwordx4 v[16:19], v[14:15], off
	v_cndmask_b32_e32 v4, v4, v5, vcc
	v_rsq_f32_e32 v4, v4
	s_nop 0
	v_mul_f32_e32 v5, 0x45800000, v4
	v_cndmask_b32_e32 v4, v4, v5, vcc
	v_pk_mul_f32 v[30:31], v[36:37], v[4:5] op_sel_hi:[1, 0]
	v_pk_mul_f32 v[32:33], v[38:39], v[4:5] op_sel_hi:[1, 0]
	v_pk_mul_f32 v[12:13], v[12:13], v[4:5] op_sel_hi:[1, 0]
	v_pk_mul_f32 v[10:11], v[10:11], v[4:5] op_sel_hi:[1, 0]
	v_pk_mul_f32 v[8:9], v[8:9], v[4:5] op_sel_hi:[1, 0]
	v_pk_mul_f32 v[6:7], v[6:7], v[4:5] op_sel_hi:[1, 0]
	v_pk_mul_f32 v[0:1], v[0:1], v[4:5] op_sel_hi:[1, 0]
	v_pk_mul_f32 v[2:3], v[2:3], v[4:5] op_sel_hi:[1, 0]
	s_waitcnt vmcnt(0)
	v_pk_fma_f32 v[16:17], v[24:25], v[30:31], v[16:17]
	v_pk_fma_f32 v[26:27], v[26:27], v[32:33], v[18:19]
	v_cvt_pk_bf16_f32 v18, v16, v17
	v_add_co_u32_e32 v16, vcc, s28, v28
	v_cvt_pk_bf16_f32 v19, v26, v27
	s_nop 1
	v_addc_co_u32_e32 v17, vcc, 0, v29, vcc
	global_store_dwordx2 v[16:17], v[18:19], off
	global_load_dwordx4 v[24:27], v[22:23], off offset:1024
	global_load_dwordx4 v[28:31], v[20:21], off offset:1024
	s_waitcnt vmcnt(0)
	v_pk_add_f32 v[18:19], v[30:31], 1.0 op_sel_hi:[1, 0]
	v_pk_add_f32 v[28:29], v[28:29], 1.0 op_sel_hi:[1, 0]
	v_pk_mul_f32 v[18:19], v[26:27], v[18:19]
	v_pk_mul_f32 v[28:29], v[24:25], v[28:29]
	global_load_dwordx4 v[24:27], v[14:15], off offset:1024
	s_waitcnt vmcnt(0)
	v_pk_fma_f32 v[12:13], v[28:29], v[12:13], v[24:25]
	v_pk_fma_f32 v[10:11], v[18:19], v[10:11], v[26:27]
	v_cvt_pk_bf16_f32 v12, v12, v13
	s_nop 0
	v_cvt_pk_bf16_f32 v13, v10, v11
	global_store_dwordx2 v[16:17], v[12:13], off offset:512
	global_load_dwordx4 v[10:13], v[22:23], off offset:2048
	s_nop 0
	global_load_dwordx4 v[24:27], v[20:21], off offset:2048
	s_waitcnt vmcnt(0)
	v_pk_add_f32 v[18:19], v[26:27], 1.0 op_sel_hi:[1, 0]
	v_pk_add_f32 v[24:25], v[24:25], 1.0 op_sel_hi:[1, 0]
	v_pk_mul_f32 v[18:19], v[12:13], v[18:19]
	v_pk_mul_f32 v[24:25], v[10:11], v[24:25]
	global_load_dwordx4 v[10:13], v[14:15], off offset:2048
	s_waitcnt vmcnt(0)
	v_pk_fma_f32 v[8:9], v[24:25], v[8:9], v[10:11]
	v_pk_fma_f32 v[6:7], v[18:19], v[6:7], v[12:13]
	v_cvt_pk_bf16_f32 v8, v8, v9
	s_nop 0
	v_cvt_pk_bf16_f32 v9, v6, v7
	global_store_dwordx2 v[16:17], v[8:9], off offset:1024
	global_load_dwordx4 v[6:9], v[22:23], off offset:3072
	s_nop 0
	global_load_dwordx4 v[10:13], v[20:21], off offset:3072
	s_waitcnt vmcnt(0)
	v_pk_add_f32 v[12:13], v[12:13], 1.0 op_sel_hi:[1, 0]
	v_pk_add_f32 v[10:11], v[10:11], 1.0 op_sel_hi:[1, 0]
	v_pk_mul_f32 v[12:13], v[8:9], v[12:13]
	v_pk_mul_f32 v[10:11], v[6:7], v[10:11]
	global_load_dwordx4 v[6:9], v[14:15], off offset:3072
	s_waitcnt vmcnt(0)
	v_pk_fma_f32 v[0:1], v[10:11], v[0:1], v[6:7]
	v_pk_fma_f32 v[2:3], v[12:13], v[2:3], v[8:9]
	v_cvt_pk_bf16_f32 v0, v0, v1
	s_nop 0
	v_cvt_pk_bf16_f32 v1, v2, v3
	global_store_dwordx2 v[16:17], v[0:1], off offset:1536
	s_cbranch_scc1 .LBB0_884
